# LDS-DMA GEMM core (2 LDS slots, register-resident stage) replacing the 4 ffn_in mainloops
# speedup vs baseline: 1.0375x; 1.0375x over previous
.LBB0_951:
	s_cmp_gt_i32 s60, 8
	s_cselect_b64 s[2:3], -1, 0
	s_cmp_lt_i32 s61, 8
	s_cselect_b64 s[4:5], -1, 0
	s_or_b64 s[2:3], s[2:3], s[4:5]
	s_and_b64 vcc, exec, s[2:3]
	s_cbranch_vccnz .LBB0_1015
	s_mov_b64 s[4:5], s[0:1]
	s_cmpk_gt_i32 s58, 0xaff
	s_cbranch_scc1 .LBB0_961
	s_load_dwordx2 s[8:9], s[4:5], 0xe0
	s_load_dword s2, s[0:1], 0xf0
	v_lshrrev_b32_e32 v10, 3, v162
	v_lshlrev_b32_e32 v0, 3, v162
	v_and_b32_e32 v0, 56, v0
	s_waitcnt lgkmcnt(0)
	s_add_u32 s4, s8, 0x8b7a100
	s_addc_u32 s5, s9, 0
	s_add_u32 s6, s8, 0x2480000
	v_mov_b32_e32 v97, 0
	v_lshlrev_b32_e32 v96, 11, v10
	s_addc_u32 s7, s9, 0
	v_lshl_add_u64 v[4:5], s[4:5], 0, v[96:97]
	v_lshlrev_b32_e32 v6, 1, v0
	v_mov_b32_e32 v7, v97
	v_xor_b32_e32 v11, v163, v162
	v_lshl_add_u64 v[98:99], v[4:5], 0, v[6:7]
	v_lshl_add_u64 v[4:5], s[6:7], 0, v[96:97]
	v_lshl_add_u64 v[100:101], v[4:5], 0, v[6:7]
	v_lshlrev_b32_e32 v5, 4, v11
	v_and_b32_e32 v8, 15, v162
	v_bfe_u32 v4, v162, 1, 3
	v_and_b32_e32 v5, 0x70, v5
	v_bfe_u32 v1, v162, 6, 1
	v_lshrrev_b32_e32 v3, 7, v162
	v_bitop3_b32 v4, v163, v4, 3 bitop3:0x6c
	v_lshl_or_b32 v152, v10, 7, v5
	v_lshlrev_b32_e32 v5, 7, v8
	v_lshl_or_b32 v6, v3, 13, v5
	v_lshl_or_b32 v5, v1, 13, v5
	v_lshlrev_b32_e32 v4, 4, v4
	v_or_b32_e32 v153, v6, v4
	v_or_b32_e32 v154, v5, v4
	v_xor_b32_e32 v4, 64, v4
	v_or_b32_e32 v155, v6, v4
	v_or_b32_e32 v156, v5, v4
	v_lshlrev_b32_e32 v157, 5, v1
	v_lshlrev_b32_e32 v4, 1, v8
	v_mov_b32_e32 v5, v97
	v_and_b32_e32 v1, 7, v162
	v_lshl_add_u64 v[4:5], s[8:9], 0, v[4:5]
	s_mov_b64 s[10:11], 0x9b7a100
	v_lshl_or_b32 v96, v1, 4, v96
	v_lshl_add_u64 v[102:103], v[4:5], 0, s[10:11]
	v_lshl_add_u64 v[4:5], s[8:9], 0, v[96:97]
	s_mov_b64 s[8:9], 0x2480200
	v_bfe_u32 v9, v162, 4, 2
	v_lshlrev_b32_e32 v2, 10, v10
	v_lshlrev_b32_e32 v3, 6, v3
	v_lshl_add_u64 v[104:105], v[4:5], 0, s[8:9]
	s_mov_b64 s[8:9], 0x8b7a300
	v_lshl_or_b32 v158, v9, 2, v3
	v_lshl_add_u64 v[106:107], v[4:5], 0, s[8:9]
	s_lshl_b32 s3, s58, 7
	s_lshl_b32 s34, s2, 7
	s_mov_b64 s[30:31], 0
	s_mov_b32 s9, 0
	s_mov_b32 s35, 0x10000
	s_mov_b32 s36, 0x30000
	s_mov_b64 s[10:11], 0x100
	s_mov_b64 s[12:13], 0x10000
	s_mov_b64 s[14:15], 0x10100
	s_mov_b64 s[16:17], 0x20000
	s_mov_b64 s[18:19], 0x20100
	s_mov_b64 s[20:21], 0x30000
	s_mov_b64 s[22:23], 0x30100
	v_lshlrev_b32_e32 v108, 1, v2
	v_mov_b32_e32 v109, v97
	v_lshlrev_b32_e32 v110, 1, v0
	v_mov_b32_e32 v111, v97
	s_mov_b64 s[24:25], 0x780
	s_movk_i32 s37, 0x1000
	s_movk_i32 s38, 0x2000
	s_movk_i32 s39, 0x4000
	s_mov_b32 s40, 0x16000
	s_mov_b32 s41, 0x17000
	s_mov_b32 s42, 0x18000
	s_mov_b32 s43, 0x1a000
	s_mov_b32 s44, 0x2c000
	s_mov_b32 s45, 0x2d000
	s_mov_b32 s46, 0x2e000
	s_mov_b32 s47, 0x42000
	s_mov_b32 s48, 0x43000
	s_mov_b32 s49, 0x44000
	s_mov_b32 s50, 0x46000
	s_mov_b32 s55, s58
	v_and_b32_e32 v240, 63, v162
	v_lshrrev_b32_e32 v247, 6, v162
	v_lshrrev_b32_e32 v242, 3, v240
	v_lshl_add_u32 v242, v247, 5, v242
	v_and_b32_e32 v243, 7, v240
	v_lshrrev_b32_e32 v244, 4, v240
	v_xor_b32_e32 v243, v243, v244
	v_lshlrev_b32_e32 v243, 4, v243
	v_mov_b32_e32 v241, 0x800
	v_mad_u32_u24 v248, v242, v241, v243
	v_xor_b32_e32 v249, 64, v248
	v_add_u32_e32 v249, 0x4000, v249
	v_add_u32_e32 v250, 0x8000, v248
	v_xor_b32_e32 v251, 64, v248
	v_add_u32_e32 v251, 0xc000, v251
	v_and_b32_e32 v241, 15, v240
	v_lshrrev_b32_e32 v242, 1, v241
	v_xor_b32_e32 v242, v242, v244
	v_lshlrev_b32_e32 v242, 4, v242
	v_lshl_or_b32 v242, v241, 7, v242
	v_lshrrev_b32_e32 v243, 1, v247
	v_lshl_or_b32 v252, v243, 13, v242
	v_xor_b32_e32 v253, 64, v252
	v_and_b32_e32 v243, 1, v247
	v_lshl_or_b32 v254, v243, 13, v242
	v_xor_b32_e32 v255, 64, v254
.LBB0_954:
	s_lshl_b32 s8, s55, 7
	s_ashr_i32 s26, s55, 6
	s_and_b32 s54, s8, 0x1f80
	s_ashr_i32 s27, s26, 31
	s_lshl_b64 s[28:29], s[26:27], 18
	s_lshl_b32 s8, s54, 11
	v_lshl_add_u64 v[112:113], v[98:99], 0, s[8:9]
	v_lshl_add_u64 v[114:115], v[100:101], 0, s[28:29]
	s_mov_b64 s[26:27], -1
	s_and_b64 vcc, exec, s[30:31]
	s_cbranch_vccnz .LBB0_956
	v_add_co_u32_e32 v28, vcc, 0x10000, v112
	s_nop 0
	v_addc_co_u32_e32 v29, vcc, 0, v113, vcc
	v_add_co_u32_e32 v36, vcc, 0x20000, v112
	s_nop 0
	v_addc_co_u32_e32 v37, vcc, 0, v113, vcc
	v_add_co_u32_e32 v44, vcc, 0x30000, v112
	s_nop 0
	v_addc_co_u32_e32 v45, vcc, 0, v113, vcc
	v_add_co_u32_e32 v52, vcc, s35, v114
	s_mov_b64 s[26:27], 0
	s_nop 0
	v_addc_co_u32_e32 v53, vcc, 0, v115, vcc
	v_add_co_u32_e32 v56, vcc, 0x20000, v114
	s_nop 0
	v_addc_co_u32_e32 v57, vcc, 0, v115, vcc
	v_add_co_u32_e32 v60, vcc, 0x30000, v114
	s_nop 1
	v_addc_co_u32_e32 v61, vcc, 0, v115, vcc
	s_nop 0
	s_nop 0
	s_nop 0
	s_nop 0
	s_nop 0
	s_nop 0
	s_nop 0
.LBB0_956:
	s_andn2_b64 vcc, exec, s[26:27]
	s_cbranch_vccnz .LBB0_958
	v_add_co_u32_e32 v0, vcc, 0x10000, v112
	s_nop 1
	v_addc_co_u32_e32 v1, vcc, 0, v113, vcc
	v_add_co_u32_e32 v2, vcc, 0x20000, v112
	s_nop 1
	v_addc_co_u32_e32 v3, vcc, 0, v113, vcc
	v_add_co_u32_e32 v0, vcc, 0x30000, v112
	v_addc_co_u32_e32 v1, vcc, 0, v113, vcc
	v_add_co_u32_e32 v2, vcc, 0x10000, v114
	s_nop 1
	v_addc_co_u32_e32 v3, vcc, 0, v115, vcc
	v_add_co_u32_e32 v0, vcc, 0x20000, v114
	s_nop 1
	v_addc_co_u32_e32 v1, vcc, 0, v115, vcc
	v_add_co_u32_e32 v2, vcc, 0x30000, v114
	s_nop 1
	v_addc_co_u32_e32 v3, vcc, 0, v115, vcc
.LBB0_958:
	s_lshl_b32 s8, s3, 11
	s_and_b32 s8, s8, 0xfc0000
	s_add_i32 s51, s55, s2
	s_cmpk_gt_i32 s51, 0xaff
	v_lshl_add_u64 v[116:117], v[106:107], 0, s[8:9]
	s_cselect_b64 s[26:27], -1, 0
	s_lshl_b32 s8, s51, 18
	s_and_b32 s8, s8, 0xfc0000
	s_add_u32 s8, s4, s8
	s_addc_u32 s59, s5, 0
	s_ashr_i32 s30, s51, 6
	s_ashr_i32 s31, s30, 31
	s_lshl_b64 s[30:31], s[30:31], 18
	s_add_u32 s62, s6, s30
	s_addc_u32 s63, s7, s31
	s_cmpk_lt_i32 s51, 0xb00
	s_cselect_b64 vcc, -1, 0
	s_and_b64 s[30:31], vcc, exec
	s_cselect_b32 s31, s59, 0
	s_cselect_b32 s30, s8, 0
	v_lshl_add_u64 v[2:3], s[30:31], 0, v[108:109]
	v_lshl_add_u64 v[0:1], v[112:113], 0, s[24:25]
	s_cselect_b32 s63, s63, 0
	s_cselect_b32 s62, s62, 0
	v_lshl_add_u64 v[2:3], v[2:3], 0, v[110:111]
	v_cndmask_b32_e32 v129, v1, v3, vcc
	v_cndmask_b32_e32 v96, v0, v2, vcc
	v_lshl_add_u64 v[0:1], s[62:63], 0, v[108:109]
	v_lshl_add_u64 v[0:1], v[0:1], 0, v[110:111]
	v_lshl_add_u64 v[2:3], v[114:115], 0, s[24:25]
	v_cndmask_b32_e32 v132, v2, v0, vcc
	v_mov_b32_e32 v0, 0
	v_lshl_add_u64 v[136:137], v[112:113], 0, s[10:11]
	v_lshl_add_u64 v[118:119], v[112:113], 0, s[12:13]
	v_lshl_add_u64 v[140:141], v[112:113], 0, s[14:15]
	v_lshl_add_u64 v[120:121], v[112:113], 0, s[16:17]
	v_lshl_add_u64 v[142:143], v[112:113], 0, s[18:19]
	v_lshl_add_u64 v[122:123], v[112:113], 0, s[20:21]
	v_lshl_add_u64 v[144:145], v[112:113], 0, s[22:23]
	v_lshl_add_u64 v[138:139], v[114:115], 0, s[10:11]
	v_lshl_add_u64 v[124:125], v[114:115], 0, s[12:13]
	v_lshl_add_u64 v[146:147], v[114:115], 0, s[14:15]
	v_lshl_add_u64 v[126:127], v[114:115], 0, s[16:17]
	v_lshl_add_u64 v[148:149], v[114:115], 0, s[18:19]
	v_lshl_add_u64 v[130:131], v[114:115], 0, s[20:21]
	v_lshl_add_u64 v[150:151], v[114:115], 0, s[22:23]
	v_cndmask_b32_e32 v133, v3, v1, vcc
	v_lshl_add_u64 v[134:135], v[104:105], 0, s[28:29]
	s_mov_b32 s28, -2
	v_mov_b32_e32 v1, v0
	v_mov_b32_e32 v2, v0
	v_mov_b32_e32 v3, v0
	v_mov_b32_e32 v16, v0
	v_mov_b32_e32 v17, v0
	v_mov_b32_e32 v18, v0
	v_mov_b32_e32 v19, v0
	v_mov_b32_e32 v4, v0
	v_mov_b32_e32 v5, v0
	v_mov_b32_e32 v6, v0
	v_mov_b32_e32 v7, v0
	v_mov_b32_e32 v20, v0
	v_mov_b32_e32 v21, v0
	v_mov_b32_e32 v22, v0
	v_mov_b32_e32 v23, v0
	v_mov_b32_e32 v12, v0
	v_mov_b32_e32 v13, v0
	v_mov_b32_e32 v14, v0
	v_mov_b32_e32 v15, v0
	v_mov_b32_e32 v24, v0
	v_mov_b32_e32 v25, v0
	v_mov_b32_e32 v26, v0
	v_mov_b32_e32 v27, v0
	v_mov_b32_e32 v8, v0
	v_mov_b32_e32 v9, v0
	v_mov_b32_e32 v10, v0
	v_mov_b32_e32 v11, v0
	v_mov_b32_e32 v32, v0
	v_mov_b32_e32 v33, v0
	v_mov_b32_e32 v34, v0
	v_mov_b32_e32 v35, v0
	v_mov_b32_e32 v64, v0
	v_mov_b32_e32 v65, v0
	v_mov_b32_e32 v66, v0
	v_mov_b32_e32 v67, v0
	v_mov_b32_e32 v72, v0
	v_mov_b32_e32 v73, v0
	v_mov_b32_e32 v74, v0
	v_mov_b32_e32 v75, v0
	v_mov_b32_e32 v68, v0
	v_mov_b32_e32 v69, v0
	v_mov_b32_e32 v70, v0
	v_mov_b32_e32 v71, v0
	v_mov_b32_e32 v76, v0
	v_mov_b32_e32 v77, v0
	v_mov_b32_e32 v78, v0
	v_mov_b32_e32 v79, v0
	v_mov_b32_e32 v80, v0
	v_mov_b32_e32 v81, v0
	v_mov_b32_e32 v82, v0
	v_mov_b32_e32 v83, v0
	v_mov_b32_e32 v88, v0
	v_mov_b32_e32 v89, v0
	v_mov_b32_e32 v90, v0
	v_mov_b32_e32 v91, v0
	v_mov_b32_e32 v84, v0
	v_mov_b32_e32 v85, v0
	v_mov_b32_e32 v86, v0
	v_mov_b32_e32 v87, v0
	v_mov_b32_e32 v92, v0
	v_mov_b32_e32 v93, v0
	v_mov_b32_e32 v94, v0
	v_mov_b32_e32 v95, v0
	v_readfirstlane_b32 s30, v112
	v_readfirstlane_b32 s31, v113
	v_readfirstlane_b32 s62, v114
	v_readfirstlane_b32 s63, v115
	v_readfirstlane_b32 s8, v247
	s_nop 3
	s_mul_i32 s59, s8, 0x4000
	s_sub_u32 s30, s30, s59
	s_subb_u32 s31, s31, 0
	s_sub_u32 s62, s62, s59
	s_subb_u32 s63, s63, 0
	s_lshl_b32 s8, s8, 12
	s_add_u32 m0, s8, 0x0
	v_mov_b32_e32 v92, 0
	global_load_lds_dwordx4 v248, s[30:31]
	v_mov_b32_e32 v93, 0
	s_add_u32 m0, s8, 0x400
	v_mov_b32_e32 v94, 0
	global_load_lds_dwordx4 v249, s[30:31]
	v_mov_b32_e32 v95, 0
	s_add_u32 m0, s8, 0x800
	v_mov_b32_e32 v84, 0
	global_load_lds_dwordx4 v250, s[30:31]
	v_mov_b32_e32 v85, 0
	s_add_u32 m0, s8, 0xc00
	v_mov_b32_e32 v86, 0
	global_load_lds_dwordx4 v251, s[30:31]
	v_mov_b32_e32 v87, 0
	s_add_u32 m0, s8, 0x8000
	v_mov_b32_e32 v88, 0
	global_load_lds_dwordx4 v248, s[62:63]
	v_mov_b32_e32 v89, 0
	s_add_u32 m0, s8, 0x8400
	v_mov_b32_e32 v90, 0
	global_load_lds_dwordx4 v249, s[62:63]
	v_mov_b32_e32 v91, 0
	s_add_u32 m0, s8, 0x8800
	v_mov_b32_e32 v80, 0
	global_load_lds_dwordx4 v250, s[62:63]
	v_mov_b32_e32 v81, 0
	s_add_u32 m0, s8, 0x8c00
	v_mov_b32_e32 v82, 0
	global_load_lds_dwordx4 v251, s[62:63]
	v_mov_b32_e32 v83, 0
	s_add_u32 s30, s30, 0x80
	s_addc_u32 s31, s31, 0
	s_add_u32 s62, s62, 0x80
	s_addc_u32 s63, s63, 0
	s_add_u32 m0, s8, 0x4000
	v_mov_b32_e32 v76, 0
	global_load_lds_dwordx4 v248, s[30:31]
	v_mov_b32_e32 v77, 0
	s_add_u32 m0, s8, 0x4400
	v_mov_b32_e32 v78, 0
	global_load_lds_dwordx4 v249, s[30:31]
	v_mov_b32_e32 v79, 0
	s_add_u32 m0, s8, 0x4800
	v_mov_b32_e32 v68, 0
	global_load_lds_dwordx4 v250, s[30:31]
	v_mov_b32_e32 v69, 0
	s_add_u32 m0, s8, 0x4c00
	v_mov_b32_e32 v70, 0
	global_load_lds_dwordx4 v251, s[30:31]
	v_mov_b32_e32 v71, 0
	s_add_u32 m0, s8, 0xc000
	v_mov_b32_e32 v72, 0
	global_load_lds_dwordx4 v248, s[62:63]
	v_mov_b32_e32 v73, 0
	s_add_u32 m0, s8, 0xc400
	v_mov_b32_e32 v74, 0
	global_load_lds_dwordx4 v249, s[62:63]
	v_mov_b32_e32 v75, 0
	s_add_u32 m0, s8, 0xc800
	v_mov_b32_e32 v64, 0
	global_load_lds_dwordx4 v250, s[62:63]
	v_mov_b32_e32 v65, 0
	s_add_u32 m0, s8, 0xcc00
	v_mov_b32_e32 v66, 0
	global_load_lds_dwordx4 v251, s[62:63]
	v_mov_b32_e32 v67, 0
	s_add_u32 s30, s30, 0x80
	s_addc_u32 s31, s31, 0
	s_add_u32 s62, s62, 0x80
	s_addc_u32 s63, s63, 0
	v_mov_b32_e32 v32, 0
	v_mov_b32_e32 v33, 0
	v_mov_b32_e32 v34, 0
	v_mov_b32_e32 v35, 0
	v_mov_b32_e32 v8, 0
	v_mov_b32_e32 v9, 0
	v_mov_b32_e32 v10, 0
	v_mov_b32_e32 v11, 0
	v_mov_b32_e32 v24, 0
	v_mov_b32_e32 v25, 0
	v_mov_b32_e32 v26, 0
	v_mov_b32_e32 v27, 0
	v_mov_b32_e32 v12, 0
	v_mov_b32_e32 v13, 0
	v_mov_b32_e32 v14, 0
	v_mov_b32_e32 v15, 0
	v_mov_b32_e32 v20, 0
	v_mov_b32_e32 v21, 0
	v_mov_b32_e32 v22, 0
	v_mov_b32_e32 v23, 0
	v_mov_b32_e32 v4, 0
	v_mov_b32_e32 v5, 0
	v_mov_b32_e32 v6, 0
	v_mov_b32_e32 v7, 0
	v_mov_b32_e32 v16, 0
	v_mov_b32_e32 v17, 0
	v_mov_b32_e32 v18, 0
	v_mov_b32_e32 v19, 0
	v_mov_b32_e32 v0, 0
	v_mov_b32_e32 v1, 0
	v_mov_b32_e32 v2, 0
	v_mov_b32_e32 v3, 0
	s_mov_b32 s32, 7
.Lg8_loop:
	s_waitcnt vmcnt(8)
	s_barrier
	ds_read_b128 v[28:31], v252 offset:0
	ds_read_b128 v[112:115], v254 offset:32768
	ds_read_b128 v[116:119], v254 offset:34816
	ds_read_b128 v[120:123], v254 offset:36864
	ds_read_b128 v[124:127], v254 offset:38912
	ds_read_b128 v[36:39], v252 offset:2048
	ds_read_b128 v[40:43], v252 offset:4096
	ds_read_b128 v[44:47], v252 offset:6144
	ds_read_b128 v[48:51], v253 offset:0
	ds_read_b128 v[132:135], v255 offset:32768
	ds_read_b128 v[136:139], v255 offset:34816
	ds_read_b128 v[140:143], v255 offset:36864
	ds_read_b128 v[144:147], v255 offset:38912
	s_waitcnt lgkmcnt(11)
	v_mfma_f32_16x16x32_bf16 v[92:95], v[28:31], v[112:115], v[92:95]
	s_waitcnt lgkmcnt(10)
	v_mfma_f32_16x16x32_bf16 v[84:87], v[28:31], v[116:119], v[84:87]
	s_waitcnt lgkmcnt(9)
	v_mfma_f32_16x16x32_bf16 v[88:91], v[28:31], v[120:123], v[88:91]
	s_waitcnt lgkmcnt(8)
	v_mfma_f32_16x16x32_bf16 v[80:83], v[28:31], v[124:127], v[80:83]
	ds_read_b128 v[52:55], v253 offset:2048
	ds_read_b128 v[56:59], v253 offset:4096
	ds_read_b128 v[60:63], v253 offset:6144
	s_waitcnt lgkmcnt(10)
	v_mfma_f32_16x16x32_bf16 v[76:79], v[36:39], v[112:115], v[76:79]
	v_mfma_f32_16x16x32_bf16 v[68:71], v[36:39], v[116:119], v[68:71]
	v_mfma_f32_16x16x32_bf16 v[72:75], v[36:39], v[120:123], v[72:75]
	v_mfma_f32_16x16x32_bf16 v[64:67], v[36:39], v[124:127], v[64:67]
	s_waitcnt lgkmcnt(9)
	v_mfma_f32_16x16x32_bf16 v[32:35], v[40:43], v[112:115], v[32:35]
	v_mfma_f32_16x16x32_bf16 v[8:11], v[40:43], v[116:119], v[8:11]
	v_mfma_f32_16x16x32_bf16 v[24:27], v[40:43], v[120:123], v[24:27]
	v_mfma_f32_16x16x32_bf16 v[12:15], v[40:43], v[124:127], v[12:15]
	s_waitcnt lgkmcnt(8)
	v_mfma_f32_16x16x32_bf16 v[20:23], v[44:47], v[112:115], v[20:23]
	v_mfma_f32_16x16x32_bf16 v[4:7], v[44:47], v[116:119], v[4:7]
	v_mfma_f32_16x16x32_bf16 v[16:19], v[44:47], v[120:123], v[16:19]
	v_mfma_f32_16x16x32_bf16 v[0:3], v[44:47], v[124:127], v[0:3]
	s_waitcnt lgkmcnt(0)
	s_barrier
	s_add_u32 m0, s8, 0x0
	v_mfma_f32_16x16x32_bf16 v[92:95], v[48:51], v[132:135], v[92:95]
	global_load_lds_dwordx4 v248, s[30:31]
	v_mfma_f32_16x16x32_bf16 v[84:87], v[48:51], v[136:139], v[84:87]
	s_add_u32 m0, s8, 0x400
	v_mfma_f32_16x16x32_bf16 v[88:91], v[48:51], v[140:143], v[88:91]
	global_load_lds_dwordx4 v249, s[30:31]
	v_mfma_f32_16x16x32_bf16 v[80:83], v[48:51], v[144:147], v[80:83]
	s_add_u32 m0, s8, 0x800
	v_mfma_f32_16x16x32_bf16 v[76:79], v[52:55], v[132:135], v[76:79]
	global_load_lds_dwordx4 v250, s[30:31]
	v_mfma_f32_16x16x32_bf16 v[68:71], v[52:55], v[136:139], v[68:71]
	s_add_u32 m0, s8, 0xc00
	v_mfma_f32_16x16x32_bf16 v[72:75], v[52:55], v[140:143], v[72:75]
	global_load_lds_dwordx4 v251, s[30:31]
	v_mfma_f32_16x16x32_bf16 v[64:67], v[52:55], v[144:147], v[64:67]
	s_add_u32 m0, s8, 0x8000
	v_mfma_f32_16x16x32_bf16 v[32:35], v[56:59], v[132:135], v[32:35]
	global_load_lds_dwordx4 v248, s[62:63]
	v_mfma_f32_16x16x32_bf16 v[8:11], v[56:59], v[136:139], v[8:11]
	s_add_u32 m0, s8, 0x8400
	v_mfma_f32_16x16x32_bf16 v[24:27], v[56:59], v[140:143], v[24:27]
	global_load_lds_dwordx4 v249, s[62:63]
	v_mfma_f32_16x16x32_bf16 v[12:15], v[56:59], v[144:147], v[12:15]
	s_add_u32 m0, s8, 0x8800
	v_mfma_f32_16x16x32_bf16 v[20:23], v[60:63], v[132:135], v[20:23]
	global_load_lds_dwordx4 v250, s[62:63]
	v_mfma_f32_16x16x32_bf16 v[4:7], v[60:63], v[136:139], v[4:7]
	s_add_u32 m0, s8, 0x8c00
	v_mfma_f32_16x16x32_bf16 v[16:19], v[60:63], v[140:143], v[16:19]
	global_load_lds_dwordx4 v251, s[62:63]
	v_mfma_f32_16x16x32_bf16 v[0:3], v[60:63], v[144:147], v[0:3]
	s_add_u32 s30, s30, 0x80
	s_addc_u32 s31, s31, 0
	s_add_u32 s62, s62, 0x80
	s_addc_u32 s63, s63, 0
	s_waitcnt vmcnt(8)
	s_barrier
	ds_read_b128 v[28:31], v252 offset:16384
	ds_read_b128 v[112:115], v254 offset:49152
	ds_read_b128 v[116:119], v254 offset:51200
	ds_read_b128 v[120:123], v254 offset:53248
	ds_read_b128 v[124:127], v254 offset:55296
	ds_read_b128 v[36:39], v252 offset:18432
	ds_read_b128 v[40:43], v252 offset:20480
	ds_read_b128 v[44:47], v252 offset:22528
	ds_read_b128 v[48:51], v253 offset:16384
	ds_read_b128 v[132:135], v255 offset:49152
	ds_read_b128 v[136:139], v255 offset:51200
	ds_read_b128 v[140:143], v255 offset:53248
	ds_read_b128 v[144:147], v255 offset:55296
	s_waitcnt lgkmcnt(11)
	v_mfma_f32_16x16x32_bf16 v[92:95], v[28:31], v[112:115], v[92:95]
	s_waitcnt lgkmcnt(10)
	v_mfma_f32_16x16x32_bf16 v[84:87], v[28:31], v[116:119], v[84:87]
	s_waitcnt lgkmcnt(9)
	v_mfma_f32_16x16x32_bf16 v[88:91], v[28:31], v[120:123], v[88:91]
	s_waitcnt lgkmcnt(8)
	v_mfma_f32_16x16x32_bf16 v[80:83], v[28:31], v[124:127], v[80:83]
	ds_read_b128 v[52:55], v253 offset:18432
	ds_read_b128 v[56:59], v253 offset:20480
	ds_read_b128 v[60:63], v253 offset:22528
	s_waitcnt lgkmcnt(10)
	v_mfma_f32_16x16x32_bf16 v[76:79], v[36:39], v[112:115], v[76:79]
	v_mfma_f32_16x16x32_bf16 v[68:71], v[36:39], v[116:119], v[68:71]
	v_mfma_f32_16x16x32_bf16 v[72:75], v[36:39], v[120:123], v[72:75]
	v_mfma_f32_16x16x32_bf16 v[64:67], v[36:39], v[124:127], v[64:67]
	s_waitcnt lgkmcnt(9)
	v_mfma_f32_16x16x32_bf16 v[32:35], v[40:43], v[112:115], v[32:35]
	v_mfma_f32_16x16x32_bf16 v[8:11], v[40:43], v[116:119], v[8:11]
	v_mfma_f32_16x16x32_bf16 v[24:27], v[40:43], v[120:123], v[24:27]
	v_mfma_f32_16x16x32_bf16 v[12:15], v[40:43], v[124:127], v[12:15]
	s_waitcnt lgkmcnt(8)
	v_mfma_f32_16x16x32_bf16 v[20:23], v[44:47], v[112:115], v[20:23]
	v_mfma_f32_16x16x32_bf16 v[4:7], v[44:47], v[116:119], v[4:7]
	v_mfma_f32_16x16x32_bf16 v[16:19], v[44:47], v[120:123], v[16:19]
	v_mfma_f32_16x16x32_bf16 v[0:3], v[44:47], v[124:127], v[0:3]
	s_waitcnt lgkmcnt(0)
	s_barrier
	s_add_u32 m0, s8, 0x4000
	v_mfma_f32_16x16x32_bf16 v[92:95], v[48:51], v[132:135], v[92:95]
	global_load_lds_dwordx4 v248, s[30:31]
	v_mfma_f32_16x16x32_bf16 v[84:87], v[48:51], v[136:139], v[84:87]
	s_add_u32 m0, s8, 0x4400
	v_mfma_f32_16x16x32_bf16 v[88:91], v[48:51], v[140:143], v[88:91]
	global_load_lds_dwordx4 v249, s[30:31]
	v_mfma_f32_16x16x32_bf16 v[80:83], v[48:51], v[144:147], v[80:83]
	s_add_u32 m0, s8, 0x4800
	v_mfma_f32_16x16x32_bf16 v[76:79], v[52:55], v[132:135], v[76:79]
	global_load_lds_dwordx4 v250, s[30:31]
	v_mfma_f32_16x16x32_bf16 v[68:71], v[52:55], v[136:139], v[68:71]
	s_add_u32 m0, s8, 0x4c00
	v_mfma_f32_16x16x32_bf16 v[72:75], v[52:55], v[140:143], v[72:75]
	global_load_lds_dwordx4 v251, s[30:31]
	v_mfma_f32_16x16x32_bf16 v[64:67], v[52:55], v[144:147], v[64:67]
	s_add_u32 m0, s8, 0xc000
	v_mfma_f32_16x16x32_bf16 v[32:35], v[56:59], v[132:135], v[32:35]
	global_load_lds_dwordx4 v248, s[62:63]
	v_mfma_f32_16x16x32_bf16 v[8:11], v[56:59], v[136:139], v[8:11]
	s_add_u32 m0, s8, 0xc400
	v_mfma_f32_16x16x32_bf16 v[24:27], v[56:59], v[140:143], v[24:27]
	global_load_lds_dwordx4 v249, s[62:63]
	v_mfma_f32_16x16x32_bf16 v[12:15], v[56:59], v[144:147], v[12:15]
	s_add_u32 m0, s8, 0xc800
	v_mfma_f32_16x16x32_bf16 v[20:23], v[60:63], v[132:135], v[20:23]
	global_load_lds_dwordx4 v250, s[62:63]
	v_mfma_f32_16x16x32_bf16 v[4:7], v[60:63], v[136:139], v[4:7]
	s_add_u32 m0, s8, 0xcc00
	v_mfma_f32_16x16x32_bf16 v[16:19], v[60:63], v[140:143], v[16:19]
	global_load_lds_dwordx4 v251, s[62:63]
	v_mfma_f32_16x16x32_bf16 v[0:3], v[60:63], v[144:147], v[0:3]
	s_add_u32 s30, s30, 0x80
	s_addc_u32 s31, s31, 0
	s_add_u32 s62, s62, 0x80
	s_addc_u32 s63, s63, 0
	s_sub_u32 s32, s32, 1
	s_cmp_lg_u32 s32, 0
	s_cbranch_scc1 .Lg8_loop
	s_waitcnt vmcnt(8)
	s_barrier
	ds_read_b128 v[28:31], v252 offset:0
	ds_read_b128 v[112:115], v254 offset:32768
	ds_read_b128 v[116:119], v254 offset:34816
	ds_read_b128 v[120:123], v254 offset:36864
	ds_read_b128 v[124:127], v254 offset:38912
	ds_read_b128 v[36:39], v252 offset:2048
	ds_read_b128 v[40:43], v252 offset:4096
	ds_read_b128 v[44:47], v252 offset:6144
	ds_read_b128 v[48:51], v253 offset:0
	ds_read_b128 v[132:135], v255 offset:32768
	ds_read_b128 v[136:139], v255 offset:34816
	ds_read_b128 v[140:143], v255 offset:36864
	ds_read_b128 v[144:147], v255 offset:38912
	s_waitcnt lgkmcnt(11)
	v_mfma_f32_16x16x32_bf16 v[92:95], v[28:31], v[112:115], v[92:95]
	s_waitcnt lgkmcnt(10)
	v_mfma_f32_16x16x32_bf16 v[84:87], v[28:31], v[116:119], v[84:87]
	s_waitcnt lgkmcnt(9)
	v_mfma_f32_16x16x32_bf16 v[88:91], v[28:31], v[120:123], v[88:91]
	s_waitcnt lgkmcnt(8)
	v_mfma_f32_16x16x32_bf16 v[80:83], v[28:31], v[124:127], v[80:83]
	ds_read_b128 v[52:55], v253 offset:2048
	ds_read_b128 v[56:59], v253 offset:4096
	ds_read_b128 v[60:63], v253 offset:6144
	s_waitcnt lgkmcnt(10)
	v_mfma_f32_16x16x32_bf16 v[76:79], v[36:39], v[112:115], v[76:79]
	v_mfma_f32_16x16x32_bf16 v[68:71], v[36:39], v[116:119], v[68:71]
	v_mfma_f32_16x16x32_bf16 v[72:75], v[36:39], v[120:123], v[72:75]
	v_mfma_f32_16x16x32_bf16 v[64:67], v[36:39], v[124:127], v[64:67]
	s_waitcnt lgkmcnt(9)
	v_mfma_f32_16x16x32_bf16 v[32:35], v[40:43], v[112:115], v[32:35]
	v_mfma_f32_16x16x32_bf16 v[8:11], v[40:43], v[116:119], v[8:11]
	v_mfma_f32_16x16x32_bf16 v[24:27], v[40:43], v[120:123], v[24:27]
	v_mfma_f32_16x16x32_bf16 v[12:15], v[40:43], v[124:127], v[12:15]
	s_waitcnt lgkmcnt(8)
	v_mfma_f32_16x16x32_bf16 v[20:23], v[44:47], v[112:115], v[20:23]
	v_mfma_f32_16x16x32_bf16 v[4:7], v[44:47], v[116:119], v[4:7]
	v_mfma_f32_16x16x32_bf16 v[16:19], v[44:47], v[120:123], v[16:19]
	v_mfma_f32_16x16x32_bf16 v[0:3], v[44:47], v[124:127], v[0:3]
	s_waitcnt lgkmcnt(0)
	s_barrier
	v_mfma_f32_16x16x32_bf16 v[92:95], v[48:51], v[132:135], v[92:95]
	v_mfma_f32_16x16x32_bf16 v[84:87], v[48:51], v[136:139], v[84:87]
	v_mfma_f32_16x16x32_bf16 v[88:91], v[48:51], v[140:143], v[88:91]
	v_mfma_f32_16x16x32_bf16 v[80:83], v[48:51], v[144:147], v[80:83]
	v_mfma_f32_16x16x32_bf16 v[76:79], v[52:55], v[132:135], v[76:79]
	v_mfma_f32_16x16x32_bf16 v[68:71], v[52:55], v[136:139], v[68:71]
	v_mfma_f32_16x16x32_bf16 v[72:75], v[52:55], v[140:143], v[72:75]
	v_mfma_f32_16x16x32_bf16 v[64:67], v[52:55], v[144:147], v[64:67]
	v_mfma_f32_16x16x32_bf16 v[32:35], v[56:59], v[132:135], v[32:35]
	v_mfma_f32_16x16x32_bf16 v[8:11], v[56:59], v[136:139], v[8:11]
	v_mfma_f32_16x16x32_bf16 v[24:27], v[56:59], v[140:143], v[24:27]
	v_mfma_f32_16x16x32_bf16 v[12:15], v[56:59], v[144:147], v[12:15]
	v_mfma_f32_16x16x32_bf16 v[20:23], v[60:63], v[132:135], v[20:23]
	v_mfma_f32_16x16x32_bf16 v[4:7], v[60:63], v[136:139], v[4:7]
	v_mfma_f32_16x16x32_bf16 v[16:19], v[60:63], v[140:143], v[16:19]
	v_mfma_f32_16x16x32_bf16 v[0:3], v[60:63], v[144:147], v[0:3]
	s_waitcnt vmcnt(0)
	s_barrier
	ds_read_b128 v[28:31], v252 offset:16384
	ds_read_b128 v[112:115], v254 offset:49152
	ds_read_b128 v[116:119], v254 offset:51200
	ds_read_b128 v[120:123], v254 offset:53248
	ds_read_b128 v[124:127], v254 offset:55296
	ds_read_b128 v[36:39], v252 offset:18432
	ds_read_b128 v[40:43], v252 offset:20480
	ds_read_b128 v[44:47], v252 offset:22528
	ds_read_b128 v[48:51], v253 offset:16384
	ds_read_b128 v[132:135], v255 offset:49152
	ds_read_b128 v[136:139], v255 offset:51200
	ds_read_b128 v[140:143], v255 offset:53248
	ds_read_b128 v[144:147], v255 offset:55296
	s_waitcnt lgkmcnt(11)
	v_mfma_f32_16x16x32_bf16 v[92:95], v[28:31], v[112:115], v[92:95]
	s_waitcnt lgkmcnt(10)
	v_mfma_f32_16x16x32_bf16 v[84:87], v[28:31], v[116:119], v[84:87]
	s_waitcnt lgkmcnt(9)
	v_mfma_f32_16x16x32_bf16 v[88:91], v[28:31], v[120:123], v[88:91]
	s_waitcnt lgkmcnt(8)
	v_mfma_f32_16x16x32_bf16 v[80:83], v[28:31], v[124:127], v[80:83]
	ds_read_b128 v[52:55], v253 offset:18432
	ds_read_b128 v[56:59], v253 offset:20480
	ds_read_b128 v[60:63], v253 offset:22528
	s_waitcnt lgkmcnt(10)
	v_mfma_f32_16x16x32_bf16 v[76:79], v[36:39], v[112:115], v[76:79]
	v_mfma_f32_16x16x32_bf16 v[68:71], v[36:39], v[116:119], v[68:71]
	v_mfma_f32_16x16x32_bf16 v[72:75], v[36:39], v[120:123], v[72:75]
	v_mfma_f32_16x16x32_bf16 v[64:67], v[36:39], v[124:127], v[64:67]
	s_waitcnt lgkmcnt(9)
	v_mfma_f32_16x16x32_bf16 v[32:35], v[40:43], v[112:115], v[32:35]
	v_mfma_f32_16x16x32_bf16 v[8:11], v[40:43], v[116:119], v[8:11]
	v_mfma_f32_16x16x32_bf16 v[24:27], v[40:43], v[120:123], v[24:27]
	v_mfma_f32_16x16x32_bf16 v[12:15], v[40:43], v[124:127], v[12:15]
	s_waitcnt lgkmcnt(8)
	v_mfma_f32_16x16x32_bf16 v[20:23], v[44:47], v[112:115], v[20:23]
	v_mfma_f32_16x16x32_bf16 v[4:7], v[44:47], v[116:119], v[4:7]
	v_mfma_f32_16x16x32_bf16 v[16:19], v[44:47], v[120:123], v[16:19]
	v_mfma_f32_16x16x32_bf16 v[0:3], v[44:47], v[124:127], v[0:3]
	s_waitcnt lgkmcnt(0)
	s_barrier
	v_mfma_f32_16x16x32_bf16 v[92:95], v[48:51], v[132:135], v[92:95]
	v_mfma_f32_16x16x32_bf16 v[84:87], v[48:51], v[136:139], v[84:87]
	v_mfma_f32_16x16x32_bf16 v[88:91], v[48:51], v[140:143], v[88:91]
	v_mfma_f32_16x16x32_bf16 v[80:83], v[48:51], v[144:147], v[80:83]
	v_mfma_f32_16x16x32_bf16 v[76:79], v[52:55], v[132:135], v[76:79]
	v_mfma_f32_16x16x32_bf16 v[68:71], v[52:55], v[136:139], v[68:71]
	v_mfma_f32_16x16x32_bf16 v[72:75], v[52:55], v[140:143], v[72:75]
	v_mfma_f32_16x16x32_bf16 v[64:67], v[52:55], v[144:147], v[64:67]
	v_mfma_f32_16x16x32_bf16 v[32:35], v[56:59], v[132:135], v[32:35]
	v_mfma_f32_16x16x32_bf16 v[8:11], v[56:59], v[136:139], v[8:11]
	v_mfma_f32_16x16x32_bf16 v[24:27], v[56:59], v[140:143], v[24:27]
	v_mfma_f32_16x16x32_bf16 v[12:15], v[56:59], v[144:147], v[12:15]
	v_mfma_f32_16x16x32_bf16 v[20:23], v[60:63], v[132:135], v[20:23]
	v_mfma_f32_16x16x32_bf16 v[4:7], v[60:63], v[136:139], v[4:7]
	v_mfma_f32_16x16x32_bf16 v[16:19], v[60:63], v[140:143], v[16:19]
	v_mfma_f32_16x16x32_bf16 v[0:3], v[60:63], v[144:147], v[0:3]
	s_nop 7
	s_nop 1
	s_waitcnt vmcnt(5)
	v_mul_f32_e32 v28, 0xbfb8aa3b, v92
	v_exp_f32_e32 v30, v28
	s_waitcnt vmcnt(4)
	v_mul_f32_e32 v36, 0xbfb8aa3b, v93
	v_exp_f32_e32 v36, v36
	s_and_b32 s8, s55, 0xffffffc0
	v_add_f32_e32 v30, 1.0, v30
	v_rcp_f32_e32 v30, v30
	v_add_f32_e32 v36, 1.0, v36
	v_or_b32_e32 v28, s8, v157
	v_rcp_f32_e32 v36, v36
	v_add_u32_e32 v31, s54, v158
	v_ashrrev_i32_e32 v29, 31, v28
	v_mul_f32_e32 v30, v92, v30
	v_lshl_add_u64 v[28:29], v[28:29], 1, v[102:103]
	v_mul_f32_e32 v30, v88, v30
	v_mul_u32_u24_e32 v96, 0x1600, v31
	v_cvt_pk_bf16_f32 v30, v30, s0
	v_lshl_add_u64 v[28:29], v[28:29], 0, v[96:97]
	global_store_short v[28:29], v30, off
	v_mul_f32_e32 v30, v93, v36
	v_mul_f32_e32 v30, v89, v30
	v_cvt_pk_bf16_f32 v36, v30, s0
	v_mul_f32_e32 v30, 0xbfb8aa3b, v94
	v_exp_f32_e32 v37, v30
	v_add_co_u32_e32 v30, vcc, s37, v28
	s_add_i32 s3, s3, s34
	s_nop 0
	v_addc_co_u32_e32 v31, vcc, 0, v29, vcc
	global_store_short v[30:31], v36, off offset:1536
	v_mul_f32_e32 v36, 0xbfb8aa3b, v95
	v_exp_f32_e32 v36, v36
	v_add_f32_e32 v37, 1.0, v37
	v_rcp_f32_e32 v37, v37
	s_mov_b64 s[30:31], -1
	v_add_f32_e32 v36, 1.0, v36
	v_rcp_f32_e32 v39, v36
	v_mul_f32_e32 v37, v94, v37
	v_mul_f32_e32 v37, v90, v37
	v_add_co_u32_e32 v36, vcc, s38, v28
	v_cvt_pk_bf16_f32 v38, v37, s0
	s_nop 0
	v_addc_co_u32_e32 v37, vcc, 0, v29, vcc
	global_store_short v[36:37], v38, off offset:3072
	v_mul_f32_e32 v38, v95, v39
	v_mul_f32_e32 v38, v91, v38
	v_cvt_pk_bf16_f32 v40, v38, s0
	v_mul_f32_e32 v38, 0xbfb8aa3b, v84
	v_exp_f32_e32 v41, v38
	v_add_co_u32_e32 v38, vcc, s39, v28
	s_mov_b32 s55, s51
	s_nop 0
	v_addc_co_u32_e32 v39, vcc, 0, v29, vcc
	global_store_short v[38:39], v40, off offset:512
	v_mul_f32_e32 v40, 0xbfb8aa3b, v85
	v_exp_f32_e32 v40, v40
	v_add_f32_e32 v41, 1.0, v41
	v_rcp_f32_e32 v41, v41
	v_add_f32_e32 v40, 1.0, v40
	v_rcp_f32_e32 v40, v40
	v_mul_f32_e32 v41, v84, v41
	v_mul_f32_e32 v41, v80, v41
	v_cvt_pk_bf16_f32 v41, v41, s0
	global_store_short v[28:29], v41, off offset:32
	v_mul_f32_e32 v41, 0xbfb8aa3b, v86
	v_mul_f32_e32 v40, v85, v40
	v_exp_f32_e32 v41, v41
	v_mul_f32_e32 v40, v81, v40
	v_cvt_pk_bf16_f32 v40, v40, s0
	global_store_short v[30:31], v40, off offset:1568
	v_mul_f32_e32 v30, 0xbfb8aa3b, v87
	v_exp_f32_e32 v30, v30
	v_add_f32_e32 v41, 1.0, v41
	v_rcp_f32_e32 v41, v41
	v_add_f32_e32 v30, 1.0, v30
	v_rcp_f32_e32 v30, v30
	v_mul_f32_e32 v31, v86, v41
	v_mul_f32_e32 v31, v82, v31
	v_cvt_pk_bf16_f32 v31, v31, s0
	global_store_short v[36:37], v31, off offset:3104
	v_mul_f32_e32 v31, 0xbfb8aa3b, v76
	v_mul_f32_e32 v30, v87, v30
	v_exp_f32_e32 v31, v31
	v_mul_f32_e32 v30, v83, v30
	v_cvt_pk_bf16_f32 v30, v30, s0
	global_store_short v[38:39], v30, off offset:544
	v_mul_f32_e32 v30, 0xbfb8aa3b, v77
	v_exp_f32_e32 v30, v30
	v_add_f32_e32 v31, 1.0, v31
	v_rcp_f32_e32 v31, v31
	v_add_f32_e32 v30, 1.0, v30
	v_rcp_f32_e32 v37, v30
	v_mul_f32_e32 v31, v76, v31
	v_mul_f32_e32 v31, v72, v31
	v_add_co_u32_e32 v30, vcc, s40, v28
	v_cvt_pk_bf16_f32 v36, v31, s0
	s_nop 0
	v_addc_co_u32_e32 v31, vcc, 0, v29, vcc
	global_store_short v[30:31], v36, off
	v_mul_f32_e32 v36, v77, v37
	v_mul_f32_e32 v36, v73, v36
	v_cvt_pk_bf16_f32 v38, v36, s0
	v_mul_f32_e32 v36, 0xbfb8aa3b, v78
	v_exp_f32_e32 v39, v36
	v_add_co_u32_e32 v36, vcc, s41, v28
	v_add_f32_e32 v39, 1.0, v39
	s_nop 0
	v_addc_co_u32_e32 v37, vcc, 0, v29, vcc
	global_store_short v[36:37], v38, off offset:1536
	v_mul_f32_e32 v38, 0xbfb8aa3b, v79
	v_exp_f32_e32 v38, v38
	v_rcp_f32_e32 v39, v39
	v_add_f32_e32 v38, 1.0, v38
	v_rcp_f32_e32 v41, v38
	v_mul_f32_e32 v39, v78, v39
	v_mul_f32_e32 v39, v74, v39
	v_add_co_u32_e32 v38, vcc, s42, v28
	v_cvt_pk_bf16_f32 v40, v39, s0
	s_nop 0
	v_addc_co_u32_e32 v39, vcc, 0, v29, vcc
	global_store_short v[38:39], v40, off offset:3072
	v_mul_f32_e32 v40, v79, v41
	v_mul_f32_e32 v40, v75, v40
	v_cvt_pk_bf16_f32 v42, v40, s0
	v_mul_f32_e32 v40, 0xbfb8aa3b, v68
	v_exp_f32_e32 v43, v40
	v_add_co_u32_e32 v40, vcc, s43, v28
	v_add_f32_e32 v43, 1.0, v43
	s_nop 0
	v_addc_co_u32_e32 v41, vcc, 0, v29, vcc
	v_rcp_f32_e32 v43, v43
	global_store_short v[40:41], v42, off offset:512
	v_mul_f32_e32 v42, 0xbfb8aa3b, v69
	v_exp_f32_e32 v42, v42
	v_mul_f32_e32 v43, v68, v43
	v_mul_f32_e32 v43, v64, v43
	v_cvt_pk_bf16_f32 v43, v43, s0
	v_add_f32_e32 v42, 1.0, v42
	v_rcp_f32_e32 v42, v42
	global_store_short v[30:31], v43, off offset:32
	v_mul_f32_e32 v30, 0xbfb8aa3b, v70
	v_exp_f32_e32 v30, v30
	v_mul_f32_e32 v31, v69, v42
	v_mul_f32_e32 v31, v65, v31
	v_cvt_pk_bf16_f32 v31, v31, s0
	v_add_f32_e32 v30, 1.0, v30
	v_rcp_f32_e32 v30, v30
	global_store_short v[36:37], v31, off offset:1568
	v_mul_f32_e32 v31, 0xbfb8aa3b, v71
	v_exp_f32_e32 v31, v31
	v_mul_f32_e32 v30, v70, v30
	v_mul_f32_e32 v30, v66, v30
	v_cvt_pk_bf16_f32 v30, v30, s0
	v_add_f32_e32 v31, 1.0, v31
	v_rcp_f32_e32 v31, v31
	global_store_short v[38:39], v30, off offset:3104
	v_mul_f32_e32 v30, 0xbfb8aa3b, v32
	v_exp_f32_e32 v30, v30
	v_mul_f32_e32 v31, v71, v31
	v_mul_f32_e32 v31, v67, v31
	v_cvt_pk_bf16_f32 v31, v31, s0
	v_add_f32_e32 v30, 1.0, v30
	v_rcp_f32_e32 v30, v30
	global_store_short v[40:41], v31, off offset:544
	v_mul_f32_e32 v31, 0xbfb8aa3b, v33
	v_exp_f32_e32 v31, v31
	v_mul_f32_e32 v30, v32, v30
	v_mul_f32_e32 v24, v24, v30
	v_cvt_pk_bf16_f32 v24, v24, s0
	v_add_f32_e32 v30, 1.0, v31
	v_rcp_f32_e32 v32, v30
	v_add_co_u32_e32 v30, vcc, s44, v28
	s_nop 1
	v_addc_co_u32_e32 v31, vcc, 0, v29, vcc
	global_store_short v[30:31], v24, off
	v_mul_f32_e32 v24, v33, v32
	v_mul_f32_e32 v24, v25, v24
	v_cvt_pk_bf16_f32 v32, v24, s0
	v_mul_f32_e32 v24, 0xbfb8aa3b, v34
	v_exp_f32_e32 v33, v24
	v_add_co_u32_e32 v24, vcc, s45, v28
	v_add_f32_e32 v33, 1.0, v33
	s_nop 0
	v_addc_co_u32_e32 v25, vcc, 0, v29, vcc
	global_store_short v[24:25], v32, off offset:1536
	v_mul_f32_e32 v32, 0xbfb8aa3b, v35
	v_exp_f32_e32 v32, v32
	v_rcp_f32_e32 v33, v33
	v_add_f32_e32 v32, 1.0, v32
	v_mul_f32_e32 v33, v34, v33
	v_rcp_f32_e32 v34, v32
	v_mul_f32_e32 v26, v26, v33
	v_add_co_u32_e32 v32, vcc, s46, v28
	v_cvt_pk_bf16_f32 v26, v26, s0
	s_nop 0
	v_addc_co_u32_e32 v33, vcc, 0, v29, vcc
	global_store_short v[32:33], v26, off offset:3072
	v_mul_f32_e32 v26, v35, v34
	v_mul_f32_e32 v26, v27, v26
	v_cvt_pk_bf16_f32 v34, v26, s0
	v_mul_f32_e32 v26, 0xbfb8aa3b, v8
	v_exp_f32_e32 v35, v26
	v_add_co_u32_e32 v26, vcc, s36, v28
	v_add_f32_e32 v35, 1.0, v35
	s_nop 0
	v_addc_co_u32_e32 v27, vcc, 0, v29, vcc
	v_rcp_f32_e32 v35, v35
	global_store_short v[26:27], v34, off offset:512
	v_mul_f32_e32 v34, 0xbfb8aa3b, v9
	v_exp_f32_e32 v34, v34
	v_mul_f32_e32 v8, v8, v35
	v_mul_f32_e32 v8, v12, v8
	v_cvt_pk_bf16_f32 v8, v8, s0
	v_add_f32_e32 v12, 1.0, v34
	v_rcp_f32_e32 v12, v12
	global_store_short v[30:31], v8, off offset:32
	v_mul_f32_e32 v8, 0xbfb8aa3b, v10
	v_exp_f32_e32 v8, v8
	v_mul_f32_e32 v9, v9, v12
	v_mul_f32_e32 v9, v13, v9
	v_cvt_pk_bf16_f32 v9, v9, s0
	v_add_f32_e32 v8, 1.0, v8
	v_rcp_f32_e32 v8, v8
	global_store_short v[24:25], v9, off offset:1568
	v_mul_f32_e32 v9, 0xbfb8aa3b, v11
	v_exp_f32_e32 v9, v9
	v_mul_f32_e32 v8, v10, v8
	v_mul_f32_e32 v8, v14, v8
	v_cvt_pk_bf16_f32 v8, v8, s0
	v_add_f32_e32 v9, 1.0, v9
	v_rcp_f32_e32 v9, v9
	global_store_short v[32:33], v8, off offset:3104
	v_mul_f32_e32 v8, 0xbfb8aa3b, v20
	v_exp_f32_e32 v8, v8
	v_mul_f32_e32 v9, v11, v9
	v_mul_f32_e32 v9, v15, v9
	v_cvt_pk_bf16_f32 v9, v9, s0
	v_add_f32_e32 v8, 1.0, v8
	v_rcp_f32_e32 v8, v8
	global_store_short v[26:27], v9, off offset:544
	v_mul_f32_e32 v9, 0xbfb8aa3b, v21
	v_exp_f32_e32 v9, v9
	v_mul_f32_e32 v8, v20, v8
	v_mul_f32_e32 v8, v16, v8
	v_cvt_pk_bf16_f32 v10, v8, s0
	v_add_f32_e32 v8, 1.0, v9
	v_rcp_f32_e32 v11, v8
	v_add_co_u32_e32 v8, vcc, s47, v28
	s_nop 1
	v_addc_co_u32_e32 v9, vcc, 0, v29, vcc
	global_store_short v[8:9], v10, off
	v_mul_f32_e32 v10, v21, v11
	v_mul_f32_e32 v10, v17, v10
	v_cvt_pk_bf16_f32 v12, v10, s0
	v_mul_f32_e32 v10, 0xbfb8aa3b, v22
	v_exp_f32_e32 v13, v10
	v_add_co_u32_e32 v10, vcc, s48, v28
	v_add_f32_e32 v13, 1.0, v13
	s_nop 0
	v_addc_co_u32_e32 v11, vcc, 0, v29, vcc
	global_store_short v[10:11], v12, off offset:1536
	v_mul_f32_e32 v12, 0xbfb8aa3b, v23
	v_exp_f32_e32 v12, v12
	v_rcp_f32_e32 v13, v13
	v_add_f32_e32 v12, 1.0, v12
	v_rcp_f32_e32 v15, v12
	v_mul_f32_e32 v13, v22, v13
	v_mul_f32_e32 v13, v18, v13
	v_add_co_u32_e32 v12, vcc, s49, v28
	v_cvt_pk_bf16_f32 v14, v13, s0
	s_nop 0
	v_addc_co_u32_e32 v13, vcc, 0, v29, vcc
	global_store_short v[12:13], v14, off offset:3072
	v_mul_f32_e32 v14, v23, v15
	v_mul_f32_e32 v14, v19, v14
	v_cvt_pk_bf16_f32 v16, v14, s0
	v_mul_f32_e32 v14, 0xbfb8aa3b, v4
	v_exp_f32_e32 v17, v14
	v_add_co_u32_e32 v14, vcc, s50, v28
	v_add_f32_e32 v17, 1.0, v17
	s_nop 0
	v_addc_co_u32_e32 v15, vcc, 0, v29, vcc
	v_rcp_f32_e32 v17, v17
	global_store_short v[14:15], v16, off offset:512
	v_mul_f32_e32 v16, 0xbfb8aa3b, v5
	v_exp_f32_e32 v16, v16
	v_mul_f32_e32 v4, v4, v17
	v_mul_f32_e32 v0, v0, v4
	v_cvt_pk_bf16_f32 v0, v0, s0
	v_add_f32_e32 v4, 1.0, v16
	v_rcp_f32_e32 v4, v4
	v_mul_f32_e32 v16, 0xbfb8aa3b, v6
	v_exp_f32_e32 v16, v16
	global_store_short v[8:9], v0, off offset:32
	v_mul_f32_e32 v0, v5, v4
	v_mul_f32_e32 v0, v1, v0
	v_add_f32_e32 v1, 1.0, v16
	v_mul_f32_e32 v4, 0xbfb8aa3b, v7
	v_rcp_f32_e32 v1, v1
	v_exp_f32_e32 v4, v4
	v_cvt_pk_bf16_f32 v0, v0, s0
	global_store_short v[10:11], v0, off offset:1568
	v_mul_f32_e32 v0, v6, v1
	v_add_f32_e32 v1, 1.0, v4
	v_rcp_f32_e32 v1, v1
	v_mul_f32_e32 v0, v2, v0
	v_cvt_pk_bf16_f32 v0, v0, s0
	global_store_short v[12:13], v0, off offset:3104
	v_mul_f32_e32 v0, v7, v1
	v_mul_f32_e32 v0, v3, v0
	v_cvt_pk_bf16_f32 v0, v0, s0
	s_andn2_b64 vcc, exec, s[26:27]
	global_store_short v[14:15], v0, off offset:544
	s_cbranch_vccnz .LBB0_954

.LBB0_1386:
	s_cmp_gt_i32 s60, 15
	s_cselect_b64 s[2:3], -1, 0
	s_cmp_lt_i32 s61, 15
	s_cselect_b64 s[4:5], -1, 0
	s_or_b64 s[2:3], s[2:3], s[4:5]
	s_and_b64 vcc, exec, s[2:3]
	s_cbranch_vccnz .LBB0_1450
	s_mov_b64 s[4:5], s[0:1]
	s_cmpk_gt_i32 s58, 0xaff
	s_cbranch_scc1 .LBB0_1396
	s_load_dwordx2 s[8:9], s[4:5], 0xe0
	s_load_dword s2, s[0:1], 0xf0
	v_lshrrev_b32_e32 v10, 3, v162
	v_lshlrev_b32_e32 v0, 3, v162
	v_and_b32_e32 v0, 56, v0
	s_waitcnt lgkmcnt(0)
	s_add_u32 s4, s8, 0x8b7a100
	s_addc_u32 s5, s9, 0
	s_add_u32 s6, s8, 0x2f80000
	v_mov_b32_e32 v97, 0
	v_lshlrev_b32_e32 v96, 11, v10
	s_addc_u32 s7, s9, 0
	v_lshl_add_u64 v[4:5], s[4:5], 0, v[96:97]
	v_lshlrev_b32_e32 v6, 1, v0
	v_mov_b32_e32 v7, v97
	v_xor_b32_e32 v11, v163, v162
	v_lshl_add_u64 v[98:99], v[4:5], 0, v[6:7]
	v_lshl_add_u64 v[4:5], s[6:7], 0, v[96:97]
	v_lshl_add_u64 v[100:101], v[4:5], 0, v[6:7]
	v_lshlrev_b32_e32 v5, 4, v11
	v_and_b32_e32 v8, 15, v162
	v_bfe_u32 v4, v162, 1, 3
	v_and_b32_e32 v5, 0x70, v5
	v_bfe_u32 v1, v162, 6, 1
	v_lshrrev_b32_e32 v3, 7, v162
	v_bitop3_b32 v4, v163, v4, 3 bitop3:0x6c
	v_lshl_or_b32 v152, v10, 7, v5
	v_lshlrev_b32_e32 v5, 7, v8
	v_lshl_or_b32 v6, v3, 13, v5
	v_lshl_or_b32 v5, v1, 13, v5
	v_lshlrev_b32_e32 v4, 4, v4
	v_or_b32_e32 v153, v6, v4
	v_or_b32_e32 v154, v5, v4
	v_xor_b32_e32 v4, 64, v4
	v_or_b32_e32 v155, v6, v4
	v_or_b32_e32 v156, v5, v4
	v_lshlrev_b32_e32 v157, 5, v1
	v_lshlrev_b32_e32 v4, 1, v8
	v_mov_b32_e32 v5, v97
	v_and_b32_e32 v1, 7, v162
	v_lshl_add_u64 v[4:5], s[8:9], 0, v[4:5]
	s_mov_b64 s[10:11], 0x9b7a100
	v_lshl_or_b32 v96, v1, 4, v96
	v_lshl_add_u64 v[102:103], v[4:5], 0, s[10:11]
	v_lshl_add_u64 v[4:5], s[8:9], 0, v[96:97]
	s_mov_b64 s[8:9], 0x2f80200
	v_bfe_u32 v9, v162, 4, 2
	v_lshlrev_b32_e32 v2, 10, v10
	v_lshlrev_b32_e32 v3, 6, v3
	v_lshl_add_u64 v[104:105], v[4:5], 0, s[8:9]
	s_mov_b64 s[8:9], 0x8b7a300
	v_lshl_or_b32 v158, v9, 2, v3
	v_lshl_add_u64 v[106:107], v[4:5], 0, s[8:9]
	s_lshl_b32 s3, s58, 7
	s_lshl_b32 s34, s2, 7
	s_mov_b64 s[30:31], 0
	s_mov_b32 s9, 0
	s_mov_b32 s35, 0x10000
	s_mov_b32 s36, 0x30000
	s_mov_b64 s[10:11], 0x100
	s_mov_b64 s[12:13], 0x10000
	s_mov_b64 s[14:15], 0x10100
	s_mov_b64 s[16:17], 0x20000
	s_mov_b64 s[18:19], 0x20100
	s_mov_b64 s[20:21], 0x30000
	s_mov_b64 s[22:23], 0x30100
	v_lshlrev_b32_e32 v108, 1, v2
	v_mov_b32_e32 v109, v97
	v_lshlrev_b32_e32 v110, 1, v0
	v_mov_b32_e32 v111, v97
	s_mov_b64 s[24:25], 0x780
	s_movk_i32 s37, 0x1000
	s_movk_i32 s38, 0x2000
	s_movk_i32 s39, 0x4000
	s_mov_b32 s40, 0x16000
	s_mov_b32 s41, 0x17000
	s_mov_b32 s42, 0x18000
	s_mov_b32 s43, 0x1a000
	s_mov_b32 s44, 0x2c000
	s_mov_b32 s45, 0x2d000
	s_mov_b32 s46, 0x2e000
	s_mov_b32 s47, 0x42000
	s_mov_b32 s48, 0x43000
	s_mov_b32 s49, 0x44000
	s_mov_b32 s50, 0x46000
	s_mov_b32 s55, s58
	v_and_b32_e32 v240, 63, v162
	v_lshrrev_b32_e32 v247, 6, v162
	v_lshrrev_b32_e32 v242, 3, v240
	v_lshl_add_u32 v242, v247, 5, v242
	v_and_b32_e32 v243, 7, v240
	v_lshrrev_b32_e32 v244, 4, v240
	v_xor_b32_e32 v243, v243, v244
	v_lshlrev_b32_e32 v243, 4, v243
	v_mov_b32_e32 v241, 0x800
	v_mad_u32_u24 v248, v242, v241, v243
	v_xor_b32_e32 v249, 64, v248
	v_add_u32_e32 v249, 0x4000, v249
	v_add_u32_e32 v250, 0x8000, v248
	v_xor_b32_e32 v251, 64, v248
	v_add_u32_e32 v251, 0xc000, v251
	v_and_b32_e32 v241, 15, v240
	v_lshrrev_b32_e32 v242, 1, v241
	v_xor_b32_e32 v242, v242, v244
	v_lshlrev_b32_e32 v242, 4, v242
	v_lshl_or_b32 v242, v241, 7, v242
	v_lshrrev_b32_e32 v243, 1, v247
	v_lshl_or_b32 v252, v243, 13, v242
	v_xor_b32_e32 v253, 64, v252
	v_and_b32_e32 v243, 1, v247
	v_lshl_or_b32 v254, v243, 13, v242
	v_xor_b32_e32 v255, 64, v254

.LBB0_2410:
	s_cmp_gt_i32 s60, 24
	s_cselect_b64 s[2:3], -1, 0
	s_cmp_lt_i32 s61, 24
	s_cselect_b64 s[4:5], -1, 0
	s_or_b64 s[2:3], s[2:3], s[4:5]
	s_and_b64 vcc, exec, s[2:3]
	s_cbranch_vccnz .LBB0_2474
	s_mov_b64 s[4:5], s[0:1]
	s_cmpk_gt_i32 s58, 0xaff
	s_cbranch_scc1 .LBB0_2420
	s_load_dwordx2 s[8:9], s[4:5], 0xe0
	s_load_dword s2, s[0:1], 0xf0
	v_lshrrev_b32_e32 v10, 3, v162
	v_lshlrev_b32_e32 v0, 3, v162
	v_and_b32_e32 v0, 56, v0
	s_waitcnt lgkmcnt(0)
	s_add_u32 s4, s8, 0x8b7a100
	s_addc_u32 s5, s9, 0
	s_add_u32 s6, s8, 0x3a80000
	v_mov_b32_e32 v97, 0
	v_lshlrev_b32_e32 v96, 11, v10
	s_addc_u32 s7, s9, 0
	v_lshl_add_u64 v[4:5], s[4:5], 0, v[96:97]
	v_lshlrev_b32_e32 v6, 1, v0
	v_mov_b32_e32 v7, v97
	v_xor_b32_e32 v11, v163, v162
	v_lshl_add_u64 v[98:99], v[4:5], 0, v[6:7]
	v_lshl_add_u64 v[4:5], s[6:7], 0, v[96:97]
	v_lshl_add_u64 v[100:101], v[4:5], 0, v[6:7]
	v_lshlrev_b32_e32 v5, 4, v11
	v_and_b32_e32 v8, 15, v162
	v_bfe_u32 v4, v162, 1, 3
	v_and_b32_e32 v5, 0x70, v5
	v_bfe_u32 v1, v162, 6, 1
	v_lshrrev_b32_e32 v3, 7, v162
	v_bitop3_b32 v4, v163, v4, 3 bitop3:0x6c
	v_lshl_or_b32 v132, v10, 7, v5
	v_lshlrev_b32_e32 v5, 7, v8
	v_lshl_or_b32 v6, v3, 13, v5
	v_lshl_or_b32 v5, v1, 13, v5
	v_lshlrev_b32_e32 v4, 4, v4
	v_or_b32_e32 v152, v6, v4
	v_or_b32_e32 v153, v5, v4
	v_xor_b32_e32 v4, 64, v4
	v_or_b32_e32 v154, v6, v4
	v_or_b32_e32 v155, v5, v4
	v_lshlrev_b32_e32 v156, 5, v1
	v_lshlrev_b32_e32 v4, 1, v8
	v_mov_b32_e32 v5, v97
	v_and_b32_e32 v1, 7, v162
	v_lshl_add_u64 v[4:5], s[8:9], 0, v[4:5]
	s_mov_b64 s[10:11], 0x9b7a100
	v_lshl_or_b32 v96, v1, 4, v96
	v_lshl_add_u64 v[102:103], v[4:5], 0, s[10:11]
	v_lshl_add_u64 v[4:5], s[8:9], 0, v[96:97]
	s_mov_b64 s[8:9], 0x3a80200
	v_bfe_u32 v9, v162, 4, 2
	v_lshlrev_b32_e32 v2, 10, v10
	v_lshlrev_b32_e32 v3, 6, v3
	v_lshl_add_u64 v[104:105], v[4:5], 0, s[8:9]
	s_mov_b64 s[8:9], 0x8b7a300
	v_lshl_or_b32 v157, v9, 2, v3
	v_lshl_add_u64 v[106:107], v[4:5], 0, s[8:9]
	s_lshl_b32 s3, s58, 7
	s_lshl_b32 s34, s2, 7
	s_mov_b64 s[30:31], 0
	s_mov_b32 s9, 0
	s_mov_b32 s35, 0x10000
	s_mov_b32 s36, 0x30000
	s_mov_b64 s[10:11], 0x100
	s_mov_b64 s[12:13], 0x10000
	s_mov_b64 s[14:15], 0x10100
	s_mov_b64 s[16:17], 0x20000
	s_mov_b64 s[18:19], 0x20100
	s_mov_b64 s[20:21], 0x30000
	s_mov_b64 s[22:23], 0x30100
	v_lshlrev_b32_e32 v108, 1, v2
	v_mov_b32_e32 v109, v97
	v_lshlrev_b32_e32 v110, 1, v0
	v_mov_b32_e32 v111, v97
	s_mov_b64 s[24:25], 0x780
	s_movk_i32 s37, 0x1000
	s_movk_i32 s38, 0x2000
	s_movk_i32 s39, 0x4000
	s_mov_b32 s40, 0x16000
	s_mov_b32 s41, 0x17000
	s_mov_b32 s42, 0x18000
	s_mov_b32 s43, 0x1a000
	s_mov_b32 s44, 0x2c000
	s_mov_b32 s45, 0x2d000
	s_mov_b32 s46, 0x2e000
	s_mov_b32 s47, 0x42000
	s_mov_b32 s48, 0x43000
	s_mov_b32 s49, 0x44000
	s_mov_b32 s50, 0x46000
	s_mov_b32 s55, s58
	v_and_b32_e32 v240, 63, v162
	v_lshrrev_b32_e32 v247, 6, v162
	v_lshrrev_b32_e32 v242, 3, v240
	v_lshl_add_u32 v242, v247, 5, v242
	v_and_b32_e32 v243, 7, v240
	v_lshrrev_b32_e32 v244, 4, v240
	v_xor_b32_e32 v243, v243, v244
	v_lshlrev_b32_e32 v243, 4, v243
	v_mov_b32_e32 v241, 0x800
	v_mad_u32_u24 v248, v242, v241, v243
	v_xor_b32_e32 v249, 64, v248
	v_add_u32_e32 v249, 0x4000, v249
	v_add_u32_e32 v250, 0x8000, v248
	v_xor_b32_e32 v251, 64, v248
	v_add_u32_e32 v251, 0xc000, v251
	v_and_b32_e32 v241, 15, v240
	v_lshrrev_b32_e32 v242, 1, v241
	v_xor_b32_e32 v242, v242, v244
	v_lshlrev_b32_e32 v242, 4, v242
	v_lshl_or_b32 v242, v241, 7, v242
	v_lshrrev_b32_e32 v243, 1, v247
	v_lshl_or_b32 v252, v243, 13, v242
	v_xor_b32_e32 v253, 64, v252
	v_and_b32_e32 v243, 1, v247
	v_lshl_or_b32 v254, v243, 13, v242
	v_xor_b32_e32 v255, 64, v254

.LBB0_2417:
	s_lshl_b32 s8, s3, 11
	s_and_b32 s8, s8, 0xfc0000
	s_add_i32 s51, s55, s2
	s_cmpk_gt_i32 s51, 0xaff
	v_lshl_add_u64 v[116:117], v[106:107], 0, s[8:9]
	s_cselect_b64 s[26:27], -1, 0
	s_lshl_b32 s8, s51, 18
	s_and_b32 s8, s8, 0xfc0000
	s_add_u32 s8, s4, s8
	s_addc_u32 s59, s5, 0
	s_ashr_i32 s30, s51, 6
	s_ashr_i32 s31, s30, 31
	s_lshl_b64 s[30:31], s[30:31], 18
	s_add_u32 s62, s6, s30
	s_addc_u32 s63, s7, s31
	s_cmpk_lt_i32 s51, 0xb00
	s_cselect_b64 vcc, -1, 0
	s_and_b64 s[30:31], vcc, exec
	s_cselect_b32 s31, s59, 0
	s_cselect_b32 s30, s8, 0
	v_lshl_add_u64 v[2:3], s[30:31], 0, v[108:109]
	v_lshl_add_u64 v[0:1], v[112:113], 0, s[24:25]
	s_cselect_b32 s63, s63, 0
	s_cselect_b32 s62, s62, 0
	v_lshl_add_u64 v[2:3], v[2:3], 0, v[110:111]
	v_cndmask_b32_e32 v131, v1, v3, vcc
	v_cndmask_b32_e32 v96, v0, v2, vcc
	v_lshl_add_u64 v[0:1], s[62:63], 0, v[108:109]
	v_lshl_add_u64 v[0:1], v[0:1], 0, v[110:111]
	v_lshl_add_u64 v[2:3], v[114:115], 0, s[24:25]
	v_cndmask_b32_e32 v130, v2, v0, vcc
	v_mov_b32_e32 v0, 0
	v_lshl_add_u64 v[136:137], v[112:113], 0, s[10:11]
	v_lshl_add_u64 v[118:119], v[112:113], 0, s[12:13]
	v_lshl_add_u64 v[140:141], v[112:113], 0, s[14:15]
	v_lshl_add_u64 v[120:121], v[112:113], 0, s[16:17]
	v_lshl_add_u64 v[142:143], v[112:113], 0, s[18:19]
	v_lshl_add_u64 v[122:123], v[112:113], 0, s[20:21]
	v_lshl_add_u64 v[144:145], v[112:113], 0, s[22:23]
	v_lshl_add_u64 v[138:139], v[114:115], 0, s[10:11]
	v_lshl_add_u64 v[124:125], v[114:115], 0, s[12:13]
	v_lshl_add_u64 v[146:147], v[114:115], 0, s[14:15]
	v_lshl_add_u64 v[126:127], v[114:115], 0, s[16:17]
	v_lshl_add_u64 v[148:149], v[114:115], 0, s[18:19]
	v_lshl_add_u64 v[128:129], v[114:115], 0, s[20:21]
	v_lshl_add_u64 v[150:151], v[114:115], 0, s[22:23]
	v_cndmask_b32_e32 v133, v3, v1, vcc
	v_lshl_add_u64 v[134:135], v[104:105], 0, s[28:29]
	s_mov_b32 s28, -2
	v_mov_b32_e32 v1, v0
	v_mov_b32_e32 v2, v0
	v_mov_b32_e32 v3, v0
	v_mov_b32_e32 v16, v0
	v_mov_b32_e32 v17, v0
	v_mov_b32_e32 v18, v0
	v_mov_b32_e32 v19, v0
	v_mov_b32_e32 v4, v0
	v_mov_b32_e32 v5, v0
	v_mov_b32_e32 v6, v0
	v_mov_b32_e32 v7, v0
	v_mov_b32_e32 v20, v0
	v_mov_b32_e32 v21, v0
	v_mov_b32_e32 v22, v0
	v_mov_b32_e32 v23, v0
	v_mov_b32_e32 v12, v0
	v_mov_b32_e32 v13, v0
	v_mov_b32_e32 v14, v0
	v_mov_b32_e32 v15, v0
	v_mov_b32_e32 v24, v0
	v_mov_b32_e32 v25, v0
	v_mov_b32_e32 v26, v0
	v_mov_b32_e32 v27, v0
	v_mov_b32_e32 v8, v0
	v_mov_b32_e32 v9, v0
	v_mov_b32_e32 v10, v0
	v_mov_b32_e32 v11, v0
	v_mov_b32_e32 v32, v0
	v_mov_b32_e32 v33, v0
	v_mov_b32_e32 v34, v0
	v_mov_b32_e32 v35, v0
	v_mov_b32_e32 v64, v0
	v_mov_b32_e32 v65, v0
	v_mov_b32_e32 v66, v0
	v_mov_b32_e32 v67, v0
	v_mov_b32_e32 v72, v0
	v_mov_b32_e32 v73, v0
	v_mov_b32_e32 v74, v0
	v_mov_b32_e32 v75, v0
	v_mov_b32_e32 v68, v0
	v_mov_b32_e32 v69, v0
	v_mov_b32_e32 v70, v0
	v_mov_b32_e32 v71, v0
	v_mov_b32_e32 v76, v0
	v_mov_b32_e32 v77, v0
	v_mov_b32_e32 v78, v0
	v_mov_b32_e32 v79, v0
	v_mov_b32_e32 v80, v0
	v_mov_b32_e32 v81, v0
	v_mov_b32_e32 v82, v0
	v_mov_b32_e32 v83, v0
	v_mov_b32_e32 v88, v0
	v_mov_b32_e32 v89, v0
	v_mov_b32_e32 v90, v0
	v_mov_b32_e32 v91, v0
	v_mov_b32_e32 v84, v0
	v_mov_b32_e32 v85, v0
	v_mov_b32_e32 v86, v0
	v_mov_b32_e32 v87, v0
	v_mov_b32_e32 v92, v0
	v_mov_b32_e32 v93, v0
	v_mov_b32_e32 v94, v0
	v_mov_b32_e32 v95, v0
	v_readfirstlane_b32 s30, v112
	v_readfirstlane_b32 s31, v113
	v_readfirstlane_b32 s62, v114
	v_readfirstlane_b32 s63, v115
	v_readfirstlane_b32 s8, v247
	s_nop 3
	s_mul_i32 s59, s8, 0x4000
	s_sub_u32 s30, s30, s59
	s_subb_u32 s31, s31, 0
	s_sub_u32 s62, s62, s59
	s_subb_u32 s63, s63, 0
	s_lshl_b32 s8, s8, 12
	s_add_u32 m0, s8, 0x0
	v_mov_b32_e32 v92, 0
	global_load_lds_dwordx4 v248, s[30:31]
	v_mov_b32_e32 v93, 0
	s_add_u32 m0, s8, 0x400
	v_mov_b32_e32 v94, 0
	global_load_lds_dwordx4 v249, s[30:31]
	v_mov_b32_e32 v95, 0
	s_add_u32 m0, s8, 0x800
	v_mov_b32_e32 v84, 0
	global_load_lds_dwordx4 v250, s[30:31]
	v_mov_b32_e32 v85, 0
	s_add_u32 m0, s8, 0xc00
	v_mov_b32_e32 v86, 0
	global_load_lds_dwordx4 v251, s[30:31]
	v_mov_b32_e32 v87, 0
	s_add_u32 m0, s8, 0x8000
	v_mov_b32_e32 v88, 0
	global_load_lds_dwordx4 v248, s[62:63]
	v_mov_b32_e32 v89, 0
	s_add_u32 m0, s8, 0x8400
	v_mov_b32_e32 v90, 0
	global_load_lds_dwordx4 v249, s[62:63]
	v_mov_b32_e32 v91, 0
	s_add_u32 m0, s8, 0x8800
	v_mov_b32_e32 v80, 0
	global_load_lds_dwordx4 v250, s[62:63]
	v_mov_b32_e32 v81, 0
	s_add_u32 m0, s8, 0x8c00
	v_mov_b32_e32 v82, 0
	global_load_lds_dwordx4 v251, s[62:63]
	v_mov_b32_e32 v83, 0
	s_add_u32 s30, s30, 0x80
	s_addc_u32 s31, s31, 0
	s_add_u32 s62, s62, 0x80
	s_addc_u32 s63, s63, 0
	s_add_u32 m0, s8, 0x4000
	v_mov_b32_e32 v76, 0
	global_load_lds_dwordx4 v248, s[30:31]
	v_mov_b32_e32 v77, 0
	s_add_u32 m0, s8, 0x4400
	v_mov_b32_e32 v78, 0
	global_load_lds_dwordx4 v249, s[30:31]
	v_mov_b32_e32 v79, 0
	s_add_u32 m0, s8, 0x4800
	v_mov_b32_e32 v68, 0
	global_load_lds_dwordx4 v250, s[30:31]
	v_mov_b32_e32 v69, 0
	s_add_u32 m0, s8, 0x4c00
	v_mov_b32_e32 v70, 0
	global_load_lds_dwordx4 v251, s[30:31]
	v_mov_b32_e32 v71, 0
	s_add_u32 m0, s8, 0xc000
	v_mov_b32_e32 v72, 0
	global_load_lds_dwordx4 v248, s[62:63]
	v_mov_b32_e32 v73, 0
	s_add_u32 m0, s8, 0xc400
	v_mov_b32_e32 v74, 0
	global_load_lds_dwordx4 v249, s[62:63]
	v_mov_b32_e32 v75, 0
	s_add_u32 m0, s8, 0xc800
	v_mov_b32_e32 v64, 0
	global_load_lds_dwordx4 v250, s[62:63]
	v_mov_b32_e32 v65, 0
	s_add_u32 m0, s8, 0xcc00
	v_mov_b32_e32 v66, 0
	global_load_lds_dwordx4 v251, s[62:63]
	v_mov_b32_e32 v67, 0
	s_add_u32 s30, s30, 0x80
	s_addc_u32 s31, s31, 0
	s_add_u32 s62, s62, 0x80
	s_addc_u32 s63, s63, 0
	v_mov_b32_e32 v32, 0
	v_mov_b32_e32 v33, 0
	v_mov_b32_e32 v34, 0
	v_mov_b32_e32 v35, 0
	v_mov_b32_e32 v8, 0
	v_mov_b32_e32 v9, 0
	v_mov_b32_e32 v10, 0
	v_mov_b32_e32 v11, 0
	v_mov_b32_e32 v24, 0
	v_mov_b32_e32 v25, 0
	v_mov_b32_e32 v26, 0
	v_mov_b32_e32 v27, 0
	v_mov_b32_e32 v12, 0
	v_mov_b32_e32 v13, 0
	v_mov_b32_e32 v14, 0
	v_mov_b32_e32 v15, 0
	v_mov_b32_e32 v20, 0
	v_mov_b32_e32 v21, 0
	v_mov_b32_e32 v22, 0
	v_mov_b32_e32 v23, 0
	v_mov_b32_e32 v4, 0
	v_mov_b32_e32 v5, 0
	v_mov_b32_e32 v6, 0
	v_mov_b32_e32 v7, 0
	v_mov_b32_e32 v16, 0
	v_mov_b32_e32 v17, 0
	v_mov_b32_e32 v18, 0
	v_mov_b32_e32 v19, 0
	v_mov_b32_e32 v0, 0
	v_mov_b32_e32 v1, 0
	v_mov_b32_e32 v2, 0
	v_mov_b32_e32 v3, 0
	s_mov_b32 s32, 7
.Lg24_loop:
	s_waitcnt vmcnt(8)
	s_barrier
	ds_read_b128 v[28:31], v252 offset:0
	ds_read_b128 v[112:115], v254 offset:32768
	ds_read_b128 v[116:119], v254 offset:34816
	ds_read_b128 v[120:123], v254 offset:36864
	ds_read_b128 v[124:127], v254 offset:38912
	ds_read_b128 v[36:39], v252 offset:2048
	ds_read_b128 v[40:43], v252 offset:4096
	ds_read_b128 v[44:47], v252 offset:6144
	ds_read_b128 v[48:51], v253 offset:0
	ds_read_b128 v[132:135], v255 offset:32768
	ds_read_b128 v[136:139], v255 offset:34816
	ds_read_b128 v[140:143], v255 offset:36864
	ds_read_b128 v[144:147], v255 offset:38912
	s_waitcnt lgkmcnt(11)
	v_mfma_f32_16x16x32_bf16 v[92:95], v[28:31], v[112:115], v[92:95]
	s_waitcnt lgkmcnt(10)
	v_mfma_f32_16x16x32_bf16 v[84:87], v[28:31], v[116:119], v[84:87]
	s_waitcnt lgkmcnt(9)
	v_mfma_f32_16x16x32_bf16 v[88:91], v[28:31], v[120:123], v[88:91]
	s_waitcnt lgkmcnt(8)
	v_mfma_f32_16x16x32_bf16 v[80:83], v[28:31], v[124:127], v[80:83]
	ds_read_b128 v[52:55], v253 offset:2048
	ds_read_b128 v[56:59], v253 offset:4096
	ds_read_b128 v[60:63], v253 offset:6144
	s_waitcnt lgkmcnt(10)
	v_mfma_f32_16x16x32_bf16 v[76:79], v[36:39], v[112:115], v[76:79]
	v_mfma_f32_16x16x32_bf16 v[68:71], v[36:39], v[116:119], v[68:71]
	v_mfma_f32_16x16x32_bf16 v[72:75], v[36:39], v[120:123], v[72:75]
	v_mfma_f32_16x16x32_bf16 v[64:67], v[36:39], v[124:127], v[64:67]
	s_waitcnt lgkmcnt(9)
	v_mfma_f32_16x16x32_bf16 v[32:35], v[40:43], v[112:115], v[32:35]
	v_mfma_f32_16x16x32_bf16 v[8:11], v[40:43], v[116:119], v[8:11]
	v_mfma_f32_16x16x32_bf16 v[24:27], v[40:43], v[120:123], v[24:27]
	v_mfma_f32_16x16x32_bf16 v[12:15], v[40:43], v[124:127], v[12:15]
	s_waitcnt lgkmcnt(8)
	v_mfma_f32_16x16x32_bf16 v[20:23], v[44:47], v[112:115], v[20:23]
	v_mfma_f32_16x16x32_bf16 v[4:7], v[44:47], v[116:119], v[4:7]
	v_mfma_f32_16x16x32_bf16 v[16:19], v[44:47], v[120:123], v[16:19]
	v_mfma_f32_16x16x32_bf16 v[0:3], v[44:47], v[124:127], v[0:3]
	s_waitcnt lgkmcnt(0)
	s_barrier
	s_add_u32 m0, s8, 0x0
	v_mfma_f32_16x16x32_bf16 v[92:95], v[48:51], v[132:135], v[92:95]
	global_load_lds_dwordx4 v248, s[30:31]
	v_mfma_f32_16x16x32_bf16 v[84:87], v[48:51], v[136:139], v[84:87]
	s_add_u32 m0, s8, 0x400
	v_mfma_f32_16x16x32_bf16 v[88:91], v[48:51], v[140:143], v[88:91]
	global_load_lds_dwordx4 v249, s[30:31]
	v_mfma_f32_16x16x32_bf16 v[80:83], v[48:51], v[144:147], v[80:83]
	s_add_u32 m0, s8, 0x800
	v_mfma_f32_16x16x32_bf16 v[76:79], v[52:55], v[132:135], v[76:79]
	global_load_lds_dwordx4 v250, s[30:31]
	v_mfma_f32_16x16x32_bf16 v[68:71], v[52:55], v[136:139], v[68:71]
	s_add_u32 m0, s8, 0xc00
	v_mfma_f32_16x16x32_bf16 v[72:75], v[52:55], v[140:143], v[72:75]
	global_load_lds_dwordx4 v251, s[30:31]
	v_mfma_f32_16x16x32_bf16 v[64:67], v[52:55], v[144:147], v[64:67]
	s_add_u32 m0, s8, 0x8000
	v_mfma_f32_16x16x32_bf16 v[32:35], v[56:59], v[132:135], v[32:35]
	global_load_lds_dwordx4 v248, s[62:63]
	v_mfma_f32_16x16x32_bf16 v[8:11], v[56:59], v[136:139], v[8:11]
	s_add_u32 m0, s8, 0x8400
	v_mfma_f32_16x16x32_bf16 v[24:27], v[56:59], v[140:143], v[24:27]
	global_load_lds_dwordx4 v249, s[62:63]
	v_mfma_f32_16x16x32_bf16 v[12:15], v[56:59], v[144:147], v[12:15]
	s_add_u32 m0, s8, 0x8800
	v_mfma_f32_16x16x32_bf16 v[20:23], v[60:63], v[132:135], v[20:23]
	global_load_lds_dwordx4 v250, s[62:63]
	v_mfma_f32_16x16x32_bf16 v[4:7], v[60:63], v[136:139], v[4:7]
	s_add_u32 m0, s8, 0x8c00
	v_mfma_f32_16x16x32_bf16 v[16:19], v[60:63], v[140:143], v[16:19]
	global_load_lds_dwordx4 v251, s[62:63]
	v_mfma_f32_16x16x32_bf16 v[0:3], v[60:63], v[144:147], v[0:3]
	s_add_u32 s30, s30, 0x80
	s_addc_u32 s31, s31, 0
	s_add_u32 s62, s62, 0x80
	s_addc_u32 s63, s63, 0
	s_waitcnt vmcnt(8)
	s_barrier
	ds_read_b128 v[28:31], v252 offset:16384
	ds_read_b128 v[112:115], v254 offset:49152
	ds_read_b128 v[116:119], v254 offset:51200
	ds_read_b128 v[120:123], v254 offset:53248
	ds_read_b128 v[124:127], v254 offset:55296
	ds_read_b128 v[36:39], v252 offset:18432
	ds_read_b128 v[40:43], v252 offset:20480
	ds_read_b128 v[44:47], v252 offset:22528
	ds_read_b128 v[48:51], v253 offset:16384
	ds_read_b128 v[132:135], v255 offset:49152
	ds_read_b128 v[136:139], v255 offset:51200
	ds_read_b128 v[140:143], v255 offset:53248
	ds_read_b128 v[144:147], v255 offset:55296
	s_waitcnt lgkmcnt(11)
	v_mfma_f32_16x16x32_bf16 v[92:95], v[28:31], v[112:115], v[92:95]
	s_waitcnt lgkmcnt(10)
	v_mfma_f32_16x16x32_bf16 v[84:87], v[28:31], v[116:119], v[84:87]
	s_waitcnt lgkmcnt(9)
	v_mfma_f32_16x16x32_bf16 v[88:91], v[28:31], v[120:123], v[88:91]
	s_waitcnt lgkmcnt(8)
	v_mfma_f32_16x16x32_bf16 v[80:83], v[28:31], v[124:127], v[80:83]
	ds_read_b128 v[52:55], v253 offset:18432
	ds_read_b128 v[56:59], v253 offset:20480
	ds_read_b128 v[60:63], v253 offset:22528
	s_waitcnt lgkmcnt(10)
	v_mfma_f32_16x16x32_bf16 v[76:79], v[36:39], v[112:115], v[76:79]
	v_mfma_f32_16x16x32_bf16 v[68:71], v[36:39], v[116:119], v[68:71]
	v_mfma_f32_16x16x32_bf16 v[72:75], v[36:39], v[120:123], v[72:75]
	v_mfma_f32_16x16x32_bf16 v[64:67], v[36:39], v[124:127], v[64:67]
	s_waitcnt lgkmcnt(9)
	v_mfma_f32_16x16x32_bf16 v[32:35], v[40:43], v[112:115], v[32:35]
	v_mfma_f32_16x16x32_bf16 v[8:11], v[40:43], v[116:119], v[8:11]
	v_mfma_f32_16x16x32_bf16 v[24:27], v[40:43], v[120:123], v[24:27]
	v_mfma_f32_16x16x32_bf16 v[12:15], v[40:43], v[124:127], v[12:15]
	s_waitcnt lgkmcnt(8)
	v_mfma_f32_16x16x32_bf16 v[20:23], v[44:47], v[112:115], v[20:23]
	v_mfma_f32_16x16x32_bf16 v[4:7], v[44:47], v[116:119], v[4:7]
	v_mfma_f32_16x16x32_bf16 v[16:19], v[44:47], v[120:123], v[16:19]
	v_mfma_f32_16x16x32_bf16 v[0:3], v[44:47], v[124:127], v[0:3]
	s_waitcnt lgkmcnt(0)
	s_barrier
	s_add_u32 m0, s8, 0x4000
	v_mfma_f32_16x16x32_bf16 v[92:95], v[48:51], v[132:135], v[92:95]
	global_load_lds_dwordx4 v248, s[30:31]
	v_mfma_f32_16x16x32_bf16 v[84:87], v[48:51], v[136:139], v[84:87]
	s_add_u32 m0, s8, 0x4400
	v_mfma_f32_16x16x32_bf16 v[88:91], v[48:51], v[140:143], v[88:91]
	global_load_lds_dwordx4 v249, s[30:31]
	v_mfma_f32_16x16x32_bf16 v[80:83], v[48:51], v[144:147], v[80:83]
	s_add_u32 m0, s8, 0x4800
	v_mfma_f32_16x16x32_bf16 v[76:79], v[52:55], v[132:135], v[76:79]
	global_load_lds_dwordx4 v250, s[30:31]
	v_mfma_f32_16x16x32_bf16 v[68:71], v[52:55], v[136:139], v[68:71]
	s_add_u32 m0, s8, 0x4c00
	v_mfma_f32_16x16x32_bf16 v[72:75], v[52:55], v[140:143], v[72:75]
	global_load_lds_dwordx4 v251, s[30:31]
	v_mfma_f32_16x16x32_bf16 v[64:67], v[52:55], v[144:147], v[64:67]
	s_add_u32 m0, s8, 0xc000
	v_mfma_f32_16x16x32_bf16 v[32:35], v[56:59], v[132:135], v[32:35]
	global_load_lds_dwordx4 v248, s[62:63]
	v_mfma_f32_16x16x32_bf16 v[8:11], v[56:59], v[136:139], v[8:11]
	s_add_u32 m0, s8, 0xc400
	v_mfma_f32_16x16x32_bf16 v[24:27], v[56:59], v[140:143], v[24:27]
	global_load_lds_dwordx4 v249, s[62:63]
	v_mfma_f32_16x16x32_bf16 v[12:15], v[56:59], v[144:147], v[12:15]
	s_add_u32 m0, s8, 0xc800
	v_mfma_f32_16x16x32_bf16 v[20:23], v[60:63], v[132:135], v[20:23]
	global_load_lds_dwordx4 v250, s[62:63]
	v_mfma_f32_16x16x32_bf16 v[4:7], v[60:63], v[136:139], v[4:7]
	s_add_u32 m0, s8, 0xcc00
	v_mfma_f32_16x16x32_bf16 v[16:19], v[60:63], v[140:143], v[16:19]
	global_load_lds_dwordx4 v251, s[62:63]
	v_mfma_f32_16x16x32_bf16 v[0:3], v[60:63], v[144:147], v[0:3]
	s_add_u32 s30, s30, 0x80
	s_addc_u32 s31, s31, 0
	s_add_u32 s62, s62, 0x80
	s_addc_u32 s63, s63, 0
	s_sub_u32 s32, s32, 1
	s_cmp_lg_u32 s32, 0
	s_cbranch_scc1 .Lg24_loop
	s_waitcnt vmcnt(8)
	s_barrier
	ds_read_b128 v[28:31], v252 offset:0
	ds_read_b128 v[112:115], v254 offset:32768
	ds_read_b128 v[116:119], v254 offset:34816
	ds_read_b128 v[120:123], v254 offset:36864
	ds_read_b128 v[124:127], v254 offset:38912
	ds_read_b128 v[36:39], v252 offset:2048
	ds_read_b128 v[40:43], v252 offset:4096
	ds_read_b128 v[44:47], v252 offset:6144
	ds_read_b128 v[48:51], v253 offset:0
	ds_read_b128 v[132:135], v255 offset:32768
	ds_read_b128 v[136:139], v255 offset:34816
	ds_read_b128 v[140:143], v255 offset:36864
	ds_read_b128 v[144:147], v255 offset:38912
	s_waitcnt lgkmcnt(11)
	v_mfma_f32_16x16x32_bf16 v[92:95], v[28:31], v[112:115], v[92:95]
	s_waitcnt lgkmcnt(10)
	v_mfma_f32_16x16x32_bf16 v[84:87], v[28:31], v[116:119], v[84:87]
	s_waitcnt lgkmcnt(9)
	v_mfma_f32_16x16x32_bf16 v[88:91], v[28:31], v[120:123], v[88:91]
	s_waitcnt lgkmcnt(8)
	v_mfma_f32_16x16x32_bf16 v[80:83], v[28:31], v[124:127], v[80:83]
	ds_read_b128 v[52:55], v253 offset:2048
	ds_read_b128 v[56:59], v253 offset:4096
	ds_read_b128 v[60:63], v253 offset:6144
	s_waitcnt lgkmcnt(10)
	v_mfma_f32_16x16x32_bf16 v[76:79], v[36:39], v[112:115], v[76:79]
	v_mfma_f32_16x16x32_bf16 v[68:71], v[36:39], v[116:119], v[68:71]
	v_mfma_f32_16x16x32_bf16 v[72:75], v[36:39], v[120:123], v[72:75]
	v_mfma_f32_16x16x32_bf16 v[64:67], v[36:39], v[124:127], v[64:67]
	s_waitcnt lgkmcnt(9)
	v_mfma_f32_16x16x32_bf16 v[32:35], v[40:43], v[112:115], v[32:35]
	v_mfma_f32_16x16x32_bf16 v[8:11], v[40:43], v[116:119], v[8:11]
	v_mfma_f32_16x16x32_bf16 v[24:27], v[40:43], v[120:123], v[24:27]
	v_mfma_f32_16x16x32_bf16 v[12:15], v[40:43], v[124:127], v[12:15]
	s_waitcnt lgkmcnt(8)
	v_mfma_f32_16x16x32_bf16 v[20:23], v[44:47], v[112:115], v[20:23]
	v_mfma_f32_16x16x32_bf16 v[4:7], v[44:47], v[116:119], v[4:7]
	v_mfma_f32_16x16x32_bf16 v[16:19], v[44:47], v[120:123], v[16:19]
	v_mfma_f32_16x16x32_bf16 v[0:3], v[44:47], v[124:127], v[0:3]
	s_waitcnt lgkmcnt(0)
	s_barrier
	v_mfma_f32_16x16x32_bf16 v[92:95], v[48:51], v[132:135], v[92:95]
	v_mfma_f32_16x16x32_bf16 v[84:87], v[48:51], v[136:139], v[84:87]
	v_mfma_f32_16x16x32_bf16 v[88:91], v[48:51], v[140:143], v[88:91]
	v_mfma_f32_16x16x32_bf16 v[80:83], v[48:51], v[144:147], v[80:83]
	v_mfma_f32_16x16x32_bf16 v[76:79], v[52:55], v[132:135], v[76:79]
	v_mfma_f32_16x16x32_bf16 v[68:71], v[52:55], v[136:139], v[68:71]
	v_mfma_f32_16x16x32_bf16 v[72:75], v[52:55], v[140:143], v[72:75]
	v_mfma_f32_16x16x32_bf16 v[64:67], v[52:55], v[144:147], v[64:67]
	v_mfma_f32_16x16x32_bf16 v[32:35], v[56:59], v[132:135], v[32:35]
	v_mfma_f32_16x16x32_bf16 v[8:11], v[56:59], v[136:139], v[8:11]
	v_mfma_f32_16x16x32_bf16 v[24:27], v[56:59], v[140:143], v[24:27]
	v_mfma_f32_16x16x32_bf16 v[12:15], v[56:59], v[144:147], v[12:15]
	v_mfma_f32_16x16x32_bf16 v[20:23], v[60:63], v[132:135], v[20:23]
	v_mfma_f32_16x16x32_bf16 v[4:7], v[60:63], v[136:139], v[4:7]
	v_mfma_f32_16x16x32_bf16 v[16:19], v[60:63], v[140:143], v[16:19]
	v_mfma_f32_16x16x32_bf16 v[0:3], v[60:63], v[144:147], v[0:3]
	s_waitcnt vmcnt(0)
	s_barrier
	ds_read_b128 v[28:31], v252 offset:16384
	ds_read_b128 v[112:115], v254 offset:49152
	ds_read_b128 v[116:119], v254 offset:51200
	ds_read_b128 v[120:123], v254 offset:53248
	ds_read_b128 v[124:127], v254 offset:55296
	ds_read_b128 v[36:39], v252 offset:18432
	ds_read_b128 v[40:43], v252 offset:20480
	ds_read_b128 v[44:47], v252 offset:22528
	ds_read_b128 v[48:51], v253 offset:16384
	ds_read_b128 v[132:135], v255 offset:49152
	ds_read_b128 v[136:139], v255 offset:51200
	ds_read_b128 v[140:143], v255 offset:53248
	ds_read_b128 v[144:147], v255 offset:55296
	s_waitcnt lgkmcnt(11)
	v_mfma_f32_16x16x32_bf16 v[92:95], v[28:31], v[112:115], v[92:95]
	s_waitcnt lgkmcnt(10)
	v_mfma_f32_16x16x32_bf16 v[84:87], v[28:31], v[116:119], v[84:87]
	s_waitcnt lgkmcnt(9)
	v_mfma_f32_16x16x32_bf16 v[88:91], v[28:31], v[120:123], v[88:91]
	s_waitcnt lgkmcnt(8)
	v_mfma_f32_16x16x32_bf16 v[80:83], v[28:31], v[124:127], v[80:83]
	ds_read_b128 v[52:55], v253 offset:18432
	ds_read_b128 v[56:59], v253 offset:20480
	ds_read_b128 v[60:63], v253 offset:22528
	s_waitcnt lgkmcnt(10)
	v_mfma_f32_16x16x32_bf16 v[76:79], v[36:39], v[112:115], v[76:79]
	v_mfma_f32_16x16x32_bf16 v[68:71], v[36:39], v[116:119], v[68:71]
	v_mfma_f32_16x16x32_bf16 v[72:75], v[36:39], v[120:123], v[72:75]
	v_mfma_f32_16x16x32_bf16 v[64:67], v[36:39], v[124:127], v[64:67]
	s_waitcnt lgkmcnt(9)
	v_mfma_f32_16x16x32_bf16 v[32:35], v[40:43], v[112:115], v[32:35]
	v_mfma_f32_16x16x32_bf16 v[8:11], v[40:43], v[116:119], v[8:11]
	v_mfma_f32_16x16x32_bf16 v[24:27], v[40:43], v[120:123], v[24:27]
	v_mfma_f32_16x16x32_bf16 v[12:15], v[40:43], v[124:127], v[12:15]
	s_waitcnt lgkmcnt(8)
	v_mfma_f32_16x16x32_bf16 v[20:23], v[44:47], v[112:115], v[20:23]
	v_mfma_f32_16x16x32_bf16 v[4:7], v[44:47], v[116:119], v[4:7]
	v_mfma_f32_16x16x32_bf16 v[16:19], v[44:47], v[120:123], v[16:19]
	v_mfma_f32_16x16x32_bf16 v[0:3], v[44:47], v[124:127], v[0:3]
	s_waitcnt lgkmcnt(0)
	s_barrier
	v_mfma_f32_16x16x32_bf16 v[92:95], v[48:51], v[132:135], v[92:95]
	v_mfma_f32_16x16x32_bf16 v[84:87], v[48:51], v[136:139], v[84:87]
	v_mfma_f32_16x16x32_bf16 v[88:91], v[48:51], v[140:143], v[88:91]
	v_mfma_f32_16x16x32_bf16 v[80:83], v[48:51], v[144:147], v[80:83]
	v_mfma_f32_16x16x32_bf16 v[76:79], v[52:55], v[132:135], v[76:79]
	v_mfma_f32_16x16x32_bf16 v[68:71], v[52:55], v[136:139], v[68:71]
	v_mfma_f32_16x16x32_bf16 v[72:75], v[52:55], v[140:143], v[72:75]
	v_mfma_f32_16x16x32_bf16 v[64:67], v[52:55], v[144:147], v[64:67]
	v_mfma_f32_16x16x32_bf16 v[32:35], v[56:59], v[132:135], v[32:35]
	v_mfma_f32_16x16x32_bf16 v[8:11], v[56:59], v[136:139], v[8:11]
	v_mfma_f32_16x16x32_bf16 v[24:27], v[56:59], v[140:143], v[24:27]
	v_mfma_f32_16x16x32_bf16 v[12:15], v[56:59], v[144:147], v[12:15]
	v_mfma_f32_16x16x32_bf16 v[20:23], v[60:63], v[132:135], v[20:23]
	v_mfma_f32_16x16x32_bf16 v[4:7], v[60:63], v[136:139], v[4:7]
	v_mfma_f32_16x16x32_bf16 v[16:19], v[60:63], v[140:143], v[16:19]
	v_mfma_f32_16x16x32_bf16 v[0:3], v[60:63], v[144:147], v[0:3]
	s_nop 7
	s_nop 1
	s_waitcnt vmcnt(5)
	v_mul_f32_e32 v28, 0xbfb8aa3b, v92
	v_exp_f32_e32 v30, v28
	s_waitcnt vmcnt(4)
	v_mul_f32_e32 v36, 0xbfb8aa3b, v93
	v_exp_f32_e32 v36, v36
	s_and_b32 s8, s55, 0xffffffc0
	v_add_f32_e32 v30, 1.0, v30
	v_rcp_f32_e32 v30, v30
	v_add_f32_e32 v36, 1.0, v36
	v_or_b32_e32 v28, s8, v156
	v_rcp_f32_e32 v36, v36
	v_add_u32_e32 v31, s54, v157
	v_ashrrev_i32_e32 v29, 31, v28
	v_mul_f32_e32 v30, v92, v30
	v_lshl_add_u64 v[28:29], v[28:29], 1, v[102:103]
	v_mul_f32_e32 v30, v88, v30
	v_mul_u32_u24_e32 v96, 0x1600, v31
	v_cvt_pk_bf16_f32 v30, v30, s0
	v_lshl_add_u64 v[28:29], v[28:29], 0, v[96:97]
	global_store_short v[28:29], v30, off
	v_mul_f32_e32 v30, v93, v36
	v_mul_f32_e32 v30, v89, v30
	v_cvt_pk_bf16_f32 v36, v30, s0
	v_mul_f32_e32 v30, 0xbfb8aa3b, v94
	v_exp_f32_e32 v37, v30
	v_add_co_u32_e32 v30, vcc, s37, v28
	s_add_i32 s3, s3, s34
	s_nop 0
	v_addc_co_u32_e32 v31, vcc, 0, v29, vcc
	global_store_short v[30:31], v36, off offset:1536
	v_mul_f32_e32 v36, 0xbfb8aa3b, v95
	v_exp_f32_e32 v36, v36
	v_add_f32_e32 v37, 1.0, v37
	v_rcp_f32_e32 v37, v37
	s_mov_b64 s[30:31], -1
	v_add_f32_e32 v36, 1.0, v36
	v_rcp_f32_e32 v39, v36
	v_mul_f32_e32 v37, v94, v37
	v_mul_f32_e32 v37, v90, v37
	v_add_co_u32_e32 v36, vcc, s38, v28
	v_cvt_pk_bf16_f32 v38, v37, s0
	s_nop 0
	v_addc_co_u32_e32 v37, vcc, 0, v29, vcc
	global_store_short v[36:37], v38, off offset:3072
	v_mul_f32_e32 v38, v95, v39
	v_mul_f32_e32 v38, v91, v38
	v_cvt_pk_bf16_f32 v40, v38, s0
	v_mul_f32_e32 v38, 0xbfb8aa3b, v84
	v_exp_f32_e32 v41, v38
	v_add_co_u32_e32 v38, vcc, s39, v28
	s_mov_b32 s55, s51
	s_nop 0
	v_addc_co_u32_e32 v39, vcc, 0, v29, vcc
	global_store_short v[38:39], v40, off offset:512
	v_mul_f32_e32 v40, 0xbfb8aa3b, v85
	v_exp_f32_e32 v40, v40
	v_add_f32_e32 v41, 1.0, v41
	v_rcp_f32_e32 v41, v41
	v_add_f32_e32 v40, 1.0, v40
	v_rcp_f32_e32 v40, v40
	v_mul_f32_e32 v41, v84, v41
	v_mul_f32_e32 v41, v80, v41
	v_cvt_pk_bf16_f32 v41, v41, s0
	global_store_short v[28:29], v41, off offset:32
	v_mul_f32_e32 v41, 0xbfb8aa3b, v86
	v_mul_f32_e32 v40, v85, v40
	v_exp_f32_e32 v41, v41
	v_mul_f32_e32 v40, v81, v40
	v_cvt_pk_bf16_f32 v40, v40, s0
	global_store_short v[30:31], v40, off offset:1568
	v_mul_f32_e32 v30, 0xbfb8aa3b, v87
	v_exp_f32_e32 v30, v30
	v_add_f32_e32 v41, 1.0, v41
	v_rcp_f32_e32 v41, v41
	v_add_f32_e32 v30, 1.0, v30
	v_rcp_f32_e32 v30, v30
	v_mul_f32_e32 v31, v86, v41
	v_mul_f32_e32 v31, v82, v31
	v_cvt_pk_bf16_f32 v31, v31, s0
	global_store_short v[36:37], v31, off offset:3104
	v_mul_f32_e32 v31, 0xbfb8aa3b, v76
	v_mul_f32_e32 v30, v87, v30
	v_exp_f32_e32 v31, v31
	v_mul_f32_e32 v30, v83, v30
	v_cvt_pk_bf16_f32 v30, v30, s0
	global_store_short v[38:39], v30, off offset:544
	v_mul_f32_e32 v30, 0xbfb8aa3b, v77
	v_exp_f32_e32 v30, v30
	v_add_f32_e32 v31, 1.0, v31
	v_rcp_f32_e32 v31, v31
	v_add_f32_e32 v30, 1.0, v30
	v_rcp_f32_e32 v37, v30
	v_mul_f32_e32 v31, v76, v31
	v_mul_f32_e32 v31, v72, v31
	v_add_co_u32_e32 v30, vcc, s40, v28
	v_cvt_pk_bf16_f32 v36, v31, s0
	s_nop 0
	v_addc_co_u32_e32 v31, vcc, 0, v29, vcc
	global_store_short v[30:31], v36, off
	v_mul_f32_e32 v36, v77, v37
	v_mul_f32_e32 v36, v73, v36
	v_cvt_pk_bf16_f32 v38, v36, s0
	v_mul_f32_e32 v36, 0xbfb8aa3b, v78
	v_exp_f32_e32 v39, v36
	v_add_co_u32_e32 v36, vcc, s41, v28
	v_add_f32_e32 v39, 1.0, v39
	s_nop 0
	v_addc_co_u32_e32 v37, vcc, 0, v29, vcc
	global_store_short v[36:37], v38, off offset:1536
	v_mul_f32_e32 v38, 0xbfb8aa3b, v79
	v_exp_f32_e32 v38, v38
	v_rcp_f32_e32 v39, v39
	v_add_f32_e32 v38, 1.0, v38
	v_rcp_f32_e32 v41, v38
	v_mul_f32_e32 v39, v78, v39
	v_mul_f32_e32 v39, v74, v39
	v_add_co_u32_e32 v38, vcc, s42, v28
	v_cvt_pk_bf16_f32 v40, v39, s0
	s_nop 0
	v_addc_co_u32_e32 v39, vcc, 0, v29, vcc
	global_store_short v[38:39], v40, off offset:3072
	v_mul_f32_e32 v40, v79, v41
	v_mul_f32_e32 v40, v75, v40
	v_cvt_pk_bf16_f32 v42, v40, s0
	v_mul_f32_e32 v40, 0xbfb8aa3b, v68
	v_exp_f32_e32 v43, v40
	v_add_co_u32_e32 v40, vcc, s43, v28
	v_add_f32_e32 v43, 1.0, v43
	s_nop 0
	v_addc_co_u32_e32 v41, vcc, 0, v29, vcc
	v_rcp_f32_e32 v43, v43
	global_store_short v[40:41], v42, off offset:512
	v_mul_f32_e32 v42, 0xbfb8aa3b, v69
	v_exp_f32_e32 v42, v42
	v_mul_f32_e32 v43, v68, v43
	v_mul_f32_e32 v43, v64, v43
	v_cvt_pk_bf16_f32 v43, v43, s0
	v_add_f32_e32 v42, 1.0, v42
	v_rcp_f32_e32 v42, v42
	global_store_short v[30:31], v43, off offset:32
	v_mul_f32_e32 v30, 0xbfb8aa3b, v70
	v_exp_f32_e32 v30, v30
	v_mul_f32_e32 v31, v69, v42
	v_mul_f32_e32 v31, v65, v31
	v_cvt_pk_bf16_f32 v31, v31, s0
	v_add_f32_e32 v30, 1.0, v30
	v_rcp_f32_e32 v30, v30
	global_store_short v[36:37], v31, off offset:1568
	v_mul_f32_e32 v31, 0xbfb8aa3b, v71
	v_exp_f32_e32 v31, v31
	v_mul_f32_e32 v30, v70, v30
	v_mul_f32_e32 v30, v66, v30
	v_cvt_pk_bf16_f32 v30, v30, s0
	v_add_f32_e32 v31, 1.0, v31
	v_rcp_f32_e32 v31, v31
	global_store_short v[38:39], v30, off offset:3104
	v_mul_f32_e32 v30, 0xbfb8aa3b, v32
	v_exp_f32_e32 v30, v30
	v_mul_f32_e32 v31, v71, v31
	v_mul_f32_e32 v31, v67, v31
	v_cvt_pk_bf16_f32 v31, v31, s0
	v_add_f32_e32 v30, 1.0, v30
	v_rcp_f32_e32 v30, v30
	global_store_short v[40:41], v31, off offset:544
	v_mul_f32_e32 v31, 0xbfb8aa3b, v33
	v_exp_f32_e32 v31, v31
	v_mul_f32_e32 v30, v32, v30
	v_mul_f32_e32 v24, v24, v30
	v_cvt_pk_bf16_f32 v24, v24, s0
	v_add_f32_e32 v30, 1.0, v31
	v_rcp_f32_e32 v32, v30
	v_add_co_u32_e32 v30, vcc, s44, v28
	s_nop 1
	v_addc_co_u32_e32 v31, vcc, 0, v29, vcc
	global_store_short v[30:31], v24, off
	v_mul_f32_e32 v24, v33, v32
	v_mul_f32_e32 v24, v25, v24
	v_cvt_pk_bf16_f32 v32, v24, s0
	v_mul_f32_e32 v24, 0xbfb8aa3b, v34
	v_exp_f32_e32 v33, v24
	v_add_co_u32_e32 v24, vcc, s45, v28
	v_add_f32_e32 v33, 1.0, v33
	s_nop 0
	v_addc_co_u32_e32 v25, vcc, 0, v29, vcc
	global_store_short v[24:25], v32, off offset:1536
	v_mul_f32_e32 v32, 0xbfb8aa3b, v35
	v_exp_f32_e32 v32, v32
	v_rcp_f32_e32 v33, v33
	v_add_f32_e32 v32, 1.0, v32
	v_mul_f32_e32 v33, v34, v33
	v_rcp_f32_e32 v34, v32
	v_mul_f32_e32 v26, v26, v33
	v_add_co_u32_e32 v32, vcc, s46, v28
	v_cvt_pk_bf16_f32 v26, v26, s0
	s_nop 0
	v_addc_co_u32_e32 v33, vcc, 0, v29, vcc
	global_store_short v[32:33], v26, off offset:3072
	v_mul_f32_e32 v26, v35, v34
	v_mul_f32_e32 v26, v27, v26
	v_cvt_pk_bf16_f32 v34, v26, s0
	v_mul_f32_e32 v26, 0xbfb8aa3b, v8
	v_exp_f32_e32 v35, v26
	v_add_co_u32_e32 v26, vcc, s36, v28
	v_add_f32_e32 v35, 1.0, v35
	s_nop 0
	v_addc_co_u32_e32 v27, vcc, 0, v29, vcc
	v_rcp_f32_e32 v35, v35
	global_store_short v[26:27], v34, off offset:512
	v_mul_f32_e32 v34, 0xbfb8aa3b, v9
	v_exp_f32_e32 v34, v34
	v_mul_f32_e32 v8, v8, v35
	v_mul_f32_e32 v8, v12, v8
	v_cvt_pk_bf16_f32 v8, v8, s0
	v_add_f32_e32 v12, 1.0, v34
	v_rcp_f32_e32 v12, v12
	global_store_short v[30:31], v8, off offset:32
	v_mul_f32_e32 v8, 0xbfb8aa3b, v10
	v_exp_f32_e32 v8, v8
	v_mul_f32_e32 v9, v9, v12
	v_mul_f32_e32 v9, v13, v9
	v_cvt_pk_bf16_f32 v9, v9, s0
	v_add_f32_e32 v8, 1.0, v8
	v_rcp_f32_e32 v8, v8
	global_store_short v[24:25], v9, off offset:1568
	v_mul_f32_e32 v9, 0xbfb8aa3b, v11
	v_exp_f32_e32 v9, v9
	v_mul_f32_e32 v8, v10, v8
	v_mul_f32_e32 v8, v14, v8
	v_cvt_pk_bf16_f32 v8, v8, s0
	v_add_f32_e32 v9, 1.0, v9
	v_rcp_f32_e32 v9, v9
	global_store_short v[32:33], v8, off offset:3104
	v_mul_f32_e32 v8, 0xbfb8aa3b, v20
	v_exp_f32_e32 v8, v8
	v_mul_f32_e32 v9, v11, v9
	v_mul_f32_e32 v9, v15, v9
	v_cvt_pk_bf16_f32 v9, v9, s0
	v_add_f32_e32 v8, 1.0, v8
	v_rcp_f32_e32 v8, v8
	global_store_short v[26:27], v9, off offset:544
	v_mul_f32_e32 v9, 0xbfb8aa3b, v21
	v_exp_f32_e32 v9, v9
	v_mul_f32_e32 v8, v20, v8
	v_mul_f32_e32 v8, v16, v8
	v_cvt_pk_bf16_f32 v10, v8, s0
	v_add_f32_e32 v8, 1.0, v9
	v_rcp_f32_e32 v11, v8
	v_add_co_u32_e32 v8, vcc, s47, v28
	s_nop 1
	v_addc_co_u32_e32 v9, vcc, 0, v29, vcc
	global_store_short v[8:9], v10, off
	v_mul_f32_e32 v10, v21, v11
	v_mul_f32_e32 v10, v17, v10
	v_cvt_pk_bf16_f32 v12, v10, s0
	v_mul_f32_e32 v10, 0xbfb8aa3b, v22
	v_exp_f32_e32 v13, v10
	v_add_co_u32_e32 v10, vcc, s48, v28
	v_add_f32_e32 v13, 1.0, v13
	s_nop 0
	v_addc_co_u32_e32 v11, vcc, 0, v29, vcc
	global_store_short v[10:11], v12, off offset:1536
	v_mul_f32_e32 v12, 0xbfb8aa3b, v23
	v_exp_f32_e32 v12, v12
	v_rcp_f32_e32 v13, v13
	v_add_f32_e32 v12, 1.0, v12
	v_rcp_f32_e32 v15, v12
	v_mul_f32_e32 v13, v22, v13
	v_mul_f32_e32 v13, v18, v13
	v_add_co_u32_e32 v12, vcc, s49, v28
	v_cvt_pk_bf16_f32 v14, v13, s0
	s_nop 0
	v_addc_co_u32_e32 v13, vcc, 0, v29, vcc
	global_store_short v[12:13], v14, off offset:3072
	v_mul_f32_e32 v14, v23, v15
	v_mul_f32_e32 v14, v19, v14
	v_cvt_pk_bf16_f32 v16, v14, s0
	v_mul_f32_e32 v14, 0xbfb8aa3b, v4
	v_exp_f32_e32 v17, v14
	v_add_co_u32_e32 v14, vcc, s50, v28
	v_add_f32_e32 v17, 1.0, v17
	s_nop 0
	v_addc_co_u32_e32 v15, vcc, 0, v29, vcc
	v_rcp_f32_e32 v17, v17
	global_store_short v[14:15], v16, off offset:512
	v_mul_f32_e32 v16, 0xbfb8aa3b, v5
	v_exp_f32_e32 v16, v16
	v_mul_f32_e32 v4, v4, v17
	v_mul_f32_e32 v0, v0, v4
	v_cvt_pk_bf16_f32 v0, v0, s0
	v_add_f32_e32 v4, 1.0, v16
	v_rcp_f32_e32 v4, v4
	v_mul_f32_e32 v16, 0xbfb8aa3b, v6
	v_exp_f32_e32 v16, v16
	global_store_short v[8:9], v0, off offset:32
	v_mul_f32_e32 v0, v5, v4
	v_mul_f32_e32 v0, v1, v0
	v_add_f32_e32 v1, 1.0, v16
	v_mul_f32_e32 v4, 0xbfb8aa3b, v7
	v_rcp_f32_e32 v1, v1
	v_exp_f32_e32 v4, v4
	v_cvt_pk_bf16_f32 v0, v0, s0
	global_store_short v[10:11], v0, off offset:1568
	v_mul_f32_e32 v0, v6, v1
	v_add_f32_e32 v1, 1.0, v4
	v_rcp_f32_e32 v1, v1
	v_mul_f32_e32 v0, v2, v0
	v_cvt_pk_bf16_f32 v0, v0, s0
	global_store_short v[12:13], v0, off offset:3104
	v_mul_f32_e32 v0, v7, v1
	v_mul_f32_e32 v0, v3, v0
	v_cvt_pk_bf16_f32 v0, v0, s0
	s_andn2_b64 vcc, exec, s[26:27]
	global_store_short v[14:15], v0, off offset:544
	s_cbranch_vccnz .LBB0_2413

.LBB0_2845:
	s_cmp_gt_i32 s60, 31
	s_cselect_b64 s[2:3], -1, 0
	s_cmp_lt_i32 s61, 31
	s_cselect_b64 s[4:5], -1, 0
	s_or_b64 s[2:3], s[2:3], s[4:5]
	s_and_b64 vcc, exec, s[2:3]
	s_cbranch_vccnz .LBB0_2909
	s_mov_b64 s[4:5], s[0:1]
	s_cmpk_gt_i32 s58, 0xaff
	s_cbranch_scc1 .LBB0_2855
	s_load_dwordx2 s[8:9], s[4:5], 0xe0
	s_load_dword s2, s[0:1], 0xf0
	v_lshrrev_b32_e32 v10, 3, v162
	v_lshlrev_b32_e32 v0, 3, v162
	v_and_b32_e32 v0, 56, v0
	s_waitcnt lgkmcnt(0)
	s_add_u32 s4, s8, 0x8b7a100
	s_addc_u32 s5, s9, 0
	s_add_u32 s6, s8, 0x4580000
	v_mov_b32_e32 v97, 0
	v_lshlrev_b32_e32 v96, 11, v10
	s_addc_u32 s7, s9, 0
	v_lshl_add_u64 v[4:5], s[4:5], 0, v[96:97]
	v_lshlrev_b32_e32 v6, 1, v0
	v_mov_b32_e32 v7, v97
	v_xor_b32_e32 v11, v163, v162
	v_lshl_add_u64 v[98:99], v[4:5], 0, v[6:7]
	v_lshl_add_u64 v[4:5], s[6:7], 0, v[96:97]
	v_lshl_add_u64 v[100:101], v[4:5], 0, v[6:7]
	v_lshlrev_b32_e32 v5, 4, v11
	v_and_b32_e32 v8, 15, v162
	v_bfe_u32 v4, v162, 1, 3
	v_and_b32_e32 v5, 0x70, v5
	v_bfe_u32 v1, v162, 6, 1
	v_lshrrev_b32_e32 v3, 7, v162
	v_bitop3_b32 v4, v163, v4, 3 bitop3:0x6c
	v_lshl_or_b32 v132, v10, 7, v5
	v_lshlrev_b32_e32 v5, 7, v8
	v_lshl_or_b32 v6, v3, 13, v5
	v_lshl_or_b32 v5, v1, 13, v5
	v_lshlrev_b32_e32 v4, 4, v4
	v_or_b32_e32 v152, v6, v4
	v_or_b32_e32 v153, v5, v4
	v_xor_b32_e32 v4, 64, v4
	v_or_b32_e32 v154, v6, v4
	v_or_b32_e32 v155, v5, v4
	v_lshlrev_b32_e32 v156, 5, v1
	v_lshlrev_b32_e32 v4, 1, v8
	v_mov_b32_e32 v5, v97
	v_and_b32_e32 v1, 7, v162
	v_lshl_add_u64 v[4:5], s[8:9], 0, v[4:5]
	s_mov_b64 s[10:11], 0x9b7a100
	v_lshl_or_b32 v96, v1, 4, v96
	v_lshl_add_u64 v[102:103], v[4:5], 0, s[10:11]
	v_lshl_add_u64 v[4:5], s[8:9], 0, v[96:97]
	s_mov_b64 s[8:9], 0x4580200
	v_bfe_u32 v9, v162, 4, 2
	v_lshlrev_b32_e32 v2, 10, v10
	v_lshlrev_b32_e32 v3, 6, v3
	v_lshl_add_u64 v[104:105], v[4:5], 0, s[8:9]
	s_mov_b64 s[8:9], 0x8b7a300
	v_lshl_or_b32 v157, v9, 2, v3
	v_lshl_add_u64 v[106:107], v[4:5], 0, s[8:9]
	s_lshl_b32 s3, s58, 7
	s_lshl_b32 s34, s2, 7
	s_mov_b64 s[30:31], 0
	s_mov_b32 s9, 0
	s_mov_b32 s35, 0x10000
	s_mov_b32 s36, 0x30000
	s_mov_b64 s[10:11], 0x100
	s_mov_b64 s[12:13], 0x10000
	s_mov_b64 s[14:15], 0x10100
	s_mov_b64 s[16:17], 0x20000
	s_mov_b64 s[18:19], 0x20100
	s_mov_b64 s[20:21], 0x30000
	s_mov_b64 s[22:23], 0x30100
	v_lshlrev_b32_e32 v108, 1, v2
	v_mov_b32_e32 v109, v97
	v_lshlrev_b32_e32 v110, 1, v0
	v_mov_b32_e32 v111, v97
	s_mov_b64 s[24:25], 0x780
	s_movk_i32 s37, 0x1000
	s_movk_i32 s38, 0x2000
	s_movk_i32 s39, 0x4000
	s_mov_b32 s40, 0x16000
	s_mov_b32 s41, 0x17000
	s_mov_b32 s42, 0x18000
	s_mov_b32 s43, 0x1a000
	s_mov_b32 s44, 0x2c000
	s_mov_b32 s45, 0x2d000
	s_mov_b32 s46, 0x2e000
	s_mov_b32 s47, 0x42000
	s_mov_b32 s48, 0x43000
	s_mov_b32 s49, 0x44000
	s_mov_b32 s50, 0x46000
	s_mov_b32 s55, s58
	v_and_b32_e32 v240, 63, v162
	v_lshrrev_b32_e32 v247, 6, v162
	v_lshrrev_b32_e32 v242, 3, v240
	v_lshl_add_u32 v242, v247, 5, v242
	v_and_b32_e32 v243, 7, v240
	v_lshrrev_b32_e32 v244, 4, v240
	v_xor_b32_e32 v243, v243, v244
	v_lshlrev_b32_e32 v243, 4, v243
	v_mov_b32_e32 v241, 0x800
	v_mad_u32_u24 v248, v242, v241, v243
	v_xor_b32_e32 v249, 64, v248
	v_add_u32_e32 v249, 0x4000, v249
	v_add_u32_e32 v250, 0x8000, v248
	v_xor_b32_e32 v251, 64, v248
	v_add_u32_e32 v251, 0xc000, v251
	v_and_b32_e32 v241, 15, v240
	v_lshrrev_b32_e32 v242, 1, v241
	v_xor_b32_e32 v242, v242, v244
	v_lshlrev_b32_e32 v242, 4, v242
	v_lshl_or_b32 v242, v241, 7, v242
	v_lshrrev_b32_e32 v243, 1, v247
	v_lshl_or_b32 v252, v243, 13, v242
	v_xor_b32_e32 v253, 64, v252
	v_and_b32_e32 v243, 1, v247
	v_lshl_or_b32 v254, v243, 13, v242
	v_xor_b32_e32 v255, 64, v254

	.amdhsa_kernel _Z4megaILb1EEv1Pii
		.amdhsa_group_segment_fixed_size 73744
		.amdhsa_private_segment_fixed_size 0
		.amdhsa_kernarg_size 496
		.amdhsa_user_sgpr_count 2
		.amdhsa_user_sgpr_dispatch_ptr 0
		.amdhsa_user_sgpr_queue_ptr 0
		.amdhsa_user_sgpr_kernarg_segment_ptr 1
		.amdhsa_user_sgpr_dispatch_id 0
		.amdhsa_user_sgpr_kernarg_preload_length 0
		.amdhsa_user_sgpr_kernarg_preload_offset 0
		.amdhsa_user_sgpr_private_segment_size 0
		.amdhsa_uses_dynamic_stack 0
		.amdhsa_enable_private_segment 0
		.amdhsa_system_sgpr_workgroup_id_x 1
		.amdhsa_system_sgpr_workgroup_id_y 0
		.amdhsa_system_sgpr_workgroup_id_z 0
		.amdhsa_system_sgpr_workgroup_info 0
		.amdhsa_system_vgpr_workitem_id 2
		.amdhsa_next_free_vgpr 256
		.amdhsa_next_free_sgpr 98
		.amdhsa_accum_offset 256
		.amdhsa_reserve_vcc 1
		.amdhsa_float_round_mode_32 0
		.amdhsa_float_round_mode_16_64 0
		.amdhsa_float_denorm_mode_32 3
		.amdhsa_float_denorm_mode_16_64 3
		.amdhsa_dx10_clamp 1
		.amdhsa_ieee_mode 1
		.amdhsa_fp16_overflow 0
		.amdhsa_tg_split 0
		.amdhsa_exception_fp_ieee_invalid_op 0
		.amdhsa_exception_fp_denorm_src 0
		.amdhsa_exception_fp_ieee_div_zero 0
		.amdhsa_exception_fp_ieee_overflow 0
		.amdhsa_exception_fp_ieee_underflow 0
		.amdhsa_exception_fp_ieee_inexact 0
		.amdhsa_exception_int_div_zero 0
	.end_amdhsa_kernel

amdhsa.kernels:
  - .agpr_count:     0
    .args:
      - .offset:         0
        .size:           232
        .value_kind:     by_value
      - .offset:         232
        .size:           4
        .value_kind:     by_value
      - .offset:         236
        .size:           4
        .value_kind:     by_value
      - .offset:         240
        .size:           4
        .value_kind:     hidden_block_count_x
      - .offset:         244
        .size:           4
        .value_kind:     hidden_block_count_y
      - .offset:         248
        .size:           4
        .value_kind:     hidden_block_count_z
      - .offset:         252
        .size:           2
        .value_kind:     hidden_group_size_x
      - .offset:         254
        .size:           2
        .value_kind:     hidden_group_size_y
      - .offset:         256
        .size:           2
        .value_kind:     hidden_group_size_z
      - .offset:         258
        .size:           2
        .value_kind:     hidden_remainder_x
      - .offset:         260
        .size:           2
        .value_kind:     hidden_remainder_y
      - .offset:         262
        .size:           2
        .value_kind:     hidden_remainder_z
      - .offset:         280
        .size:           8
        .value_kind:     hidden_global_offset_x
      - .offset:         288
        .size:           8
        .value_kind:     hidden_global_offset_y
      - .offset:         296
        .size:           8
        .value_kind:     hidden_global_offset_z
      - .offset:         304
        .size:           2
        .value_kind:     hidden_grid_dims
      - .offset:         328
        .size:           8
        .value_kind:     hidden_multigrid_sync_arg
    .group_segment_fixed_size: 73744
    .kernarg_segment_align: 8
    .kernarg_segment_size: 496
    .language:       OpenCL C
    .language_version:
      - 2
      - 0
    .max_flat_workgroup_size: 256
    .name:           _Z4megaILb1EEv1Pii
    .private_segment_fixed_size: 0
    .sgpr_count:     104
    .sgpr_spill_count: 0
    .symbol:         _Z4megaILb1EEv1Pii.kd
    .uniform_work_group_size: 1
    .uses_dynamic_stack: false
    .vgpr_count:     256
    .vgpr_spill_count: 0
    .wavefront_size: 64
